# PH4: streaming global loads of the attention/pool/convert workers and of the scan carry sc1 (agent scope, bypass the CU L1)
# speedup vs baseline: 1.0053x; 1.0036x over previous
.LBB0_771:
	s_cmpk_gt_i32 s9, 0x43f
	s_mov_b64 s[0:1], -1
	s_cbranch_scc0 .LBB0_820
	s_cmpk_gt_u32 s9, 0x54f
	s_cbranch_scc0 .LBB0_802
	s_add_i32 s2, s9, 0xfffffab0
	s_cmpk_gt_u32 s2, 0x13f
	s_cbranch_scc0 .LBB0_783
	s_cmpk_gt_u32 s2, 0x1bf
	s_cbranch_scc0 .LBB0_780
	s_lshl_b32 s3, s2, 6
	s_cmpk_gt_u32 s2, 0x3bf
	s_cbranch_scc0 .LBB0_777
	s_lshl_b32 s0, s2, 3
	s_and_b32 s0, s0, 0x7fffff80
	v_mov_b32_e32 v10, v133
	s_add_i32 s10, s0, 0xffffe200
	s_and_b32 s0, s3, 0x3c0
	s_lshl_b32 s1, s0, 2
	v_ashrrev_i32_e32 v8, 4, v10
	v_readlane_b32 s4, v207, 12
	v_add_u32_e32 v2, s10, v8
	s_add_u32 s4, s4, s1
	v_readlane_b32 s1, v207, 13
	v_lshlrev_b32_e32 v0, 4, v10
	s_addc_u32 s5, s1, 0
	v_and_b32_e32 v0, 0xf0, v0
	v_ashrrev_i32_e32 v3, 31, v2
	v_lshl_add_u64 v[4:5], s[4:5], 0, v[0:1]
	v_lshlrev_b64 v[2:3], 12, v[2:3]
	v_lshl_add_u64 v[6:7], v[4:5], 0, v[2:3]
	global_load_dwordx4 v[2:5], v[6:7], off sc1
	s_movk_i32 s1, 0x104
	v_mad_u64_u32 v[8:9], s[4:5], v8, s1, v[0:1]
	v_add_u32_e32 v0, 0x1040, v8
	s_mov_b32 s4, 0x40000
	v_readlane_b32 s6, v207, 14
	s_waitcnt vmcnt(0)
	ds_write2_b32 v8, v2, v3 offset1:1
	ds_write2_b32 v8, v4, v5 offset0:2 offset1:3
	v_add_co_u32_e32 v2, vcc, s56, v6
	s_nop 1
	v_addc_co_u32_e32 v3, vcc, 0, v7, vcc
	global_load_dwordx4 v[2:5], v[2:3], off sc1
	s_waitcnt vmcnt(0)
	ds_write2_b32 v0, v2, v3 offset1:1
	v_add_co_u32_e32 v2, vcc, s57, v6
	v_add_u32_e32 v0, 0x1048, v8
	s_nop 0
	v_addc_co_u32_e32 v3, vcc, 0, v7, vcc
	ds_write2_b32 v0, v4, v5 offset1:1
	global_load_dwordx4 v[2:5], v[2:3], off sc1
	v_add_u32_e32 v0, 0x2080, v8
	s_waitcnt vmcnt(0)
	ds_write2_b32 v0, v2, v3 offset1:1
	v_add_co_u32_e32 v2, vcc, s58, v6
	v_add_u32_e32 v0, 0x2088, v8
	s_nop 0
	v_addc_co_u32_e32 v3, vcc, 0, v7, vcc
	ds_write2_b32 v0, v4, v5 offset1:1
	global_load_dwordx4 v[2:5], v[2:3], off sc1
	v_add_u32_e32 v0, 0x30c0, v8
	s_waitcnt vmcnt(0)
	ds_write2_b32 v0, v2, v3 offset1:1
	v_add_co_u32_e32 v2, vcc, s4, v6
	v_add_u32_e32 v0, 0x30c8, v8
	s_nop 0
	v_addc_co_u32_e32 v3, vcc, 0, v7, vcc
	ds_write2_b32 v0, v4, v5 offset1:1
	global_load_dwordx4 v[2:5], v[2:3], off sc1
	v_add_u32_e32 v0, 0x4100, v8
	s_mov_b32 s4, 0x50000
	s_waitcnt vmcnt(0)
	ds_write2_b32 v0, v2, v3 offset1:1
	v_add_co_u32_e32 v2, vcc, s4, v6
	v_add_u32_e32 v0, 0x4108, v8
	s_nop 0
	v_addc_co_u32_e32 v3, vcc, 0, v7, vcc
	ds_write2_b32 v0, v4, v5 offset1:1
	global_load_dwordx4 v[2:5], v[2:3], off sc1
	v_add_u32_e32 v0, 0x5140, v8
	s_mov_b32 s4, 0x60000
	s_waitcnt vmcnt(0)
	ds_write2_b32 v0, v2, v3 offset1:1
	v_add_co_u32_e32 v2, vcc, s4, v6
	v_add_u32_e32 v0, 0x5148, v8
	s_nop 0
	v_addc_co_u32_e32 v3, vcc, 0, v7, vcc
	ds_write2_b32 v0, v4, v5 offset1:1
	global_load_dwordx4 v[2:5], v[2:3], off sc1
	v_add_u32_e32 v0, 0x6180, v8
	s_mov_b32 s4, 0x70000
	s_waitcnt vmcnt(0)
	ds_write2_b32 v0, v2, v3 offset1:1
	v_add_co_u32_e32 v2, vcc, s4, v6
	v_add_u32_e32 v0, 0x6188, v8
	s_nop 0
	v_addc_co_u32_e32 v3, vcc, 0, v7, vcc
	ds_write2_b32 v0, v4, v5 offset1:1
	global_load_dwordx4 v[2:5], v[2:3], off sc1
	v_add_u32_e32 v0, 0x71c0, v8
	s_lshl_b64 s[4:5], s[10:11], 1
	s_add_u32 s4, s6, s4
	v_readlane_b32 s6, v207, 15
	s_addc_u32 s5, s6, s5
	s_waitcnt vmcnt(0)
	ds_write2_b32 v0, v2, v3 offset1:1
	v_add_u32_e32 v0, 0x71c8, v8
	ds_write2_b32 v0, v4, v5 offset1:1
	v_ashrrev_i32_e32 v0, 3, v10
	v_lshlrev_b32_e32 v2, 3, v10
	v_and_b32_e32 v26, 56, v2
	v_lshlrev_b32_e32 v27, 2, v0
	v_mad_u32_u24 v4, v26, s1, v27
	v_add_u32_e32 v5, 0x400, v4
	s_waitcnt lgkmcnt(0)
	s_barrier
	ds_read2_b32 v[6:7], v4 offset1:32
	ds_read2_b32 v[8:9], v4 offset0:65 offset1:97
	ds_read2_b32 v[10:11], v4 offset0:130 offset1:162
	ds_read2_b32 v[12:13], v4 offset0:195 offset1:227
	ds_read2_b32 v[14:15], v5 offset0:4 offset1:36
	ds_read2_b32 v[16:17], v5 offset0:69 offset1:101
	ds_read2_b32 v[18:19], v5 offset0:134 offset1:166
	ds_read2_b32 v[20:21], v5 offset0:199 offset1:231
	v_add_u32_e32 v22, s0, v0
	v_ashrrev_i32_e32 v23, 31, v22
	v_lshlrev_b64 v[24:25], 13, v[22:23]
	v_lshl_add_u64 v[24:25], s[4:5], 0, v[24:25]
	v_lshlrev_b32_e32 v0, 1, v26
	s_waitcnt lgkmcnt(6)
	v_cvt_pk_bf16_f32 v2, v6, v8
	s_waitcnt lgkmcnt(4)
	v_cvt_pk_bf16_f32 v3, v10, v12
	s_waitcnt lgkmcnt(2)
	v_cvt_pk_bf16_f32 v4, v14, v16
	s_waitcnt lgkmcnt(0)
	v_cvt_pk_bf16_f32 v5, v18, v20
	v_lshl_add_u64 v[24:25], v[24:25], 0, v[0:1]
	v_add_u32_e32 v6, 32, v22
	global_store_dwordx4 v[24:25], v[2:5], off
	s_nop 1
	v_cvt_pk_bf16_f32 v2, v7, v9
	v_ashrrev_i32_e32 v7, 31, v6
	v_lshlrev_b64 v[6:7], 13, v[6:7]
	v_lshl_add_u64 v[6:7], s[4:5], 0, v[6:7]
	v_cvt_pk_bf16_f32 v3, v11, v13
	v_cvt_pk_bf16_f32 v4, v15, v17
	v_cvt_pk_bf16_f32 v5, v19, v21
	v_lshl_add_u64 v[6:7], v[6:7], 0, v[0:1]
	v_or_b32_e32 v0, 64, v26
	global_store_dwordx4 v[6:7], v[2:5], off
	v_mad_u32_u24 v0, v0, s1, v27
	ds_read2_b32 v[8:9], v0 offset1:32
	ds_read2_b32 v[10:11], v0 offset0:65 offset1:97
	ds_read2_b32 v[12:13], v0 offset0:130 offset1:162
	ds_read2_b32 v[14:15], v0 offset0:195 offset1:227
	v_add_u32_e32 v0, 0x400, v0
	ds_read2_b32 v[16:17], v0 offset0:4 offset1:36
	ds_read2_b32 v[18:19], v0 offset0:69 offset1:101
	ds_read2_b32 v[20:21], v0 offset0:134 offset1:166
	ds_read2_b32 v[22:23], v0 offset0:199 offset1:231
	s_waitcnt lgkmcnt(6)
	v_cvt_pk_bf16_f32 v2, v8, v10
	s_waitcnt lgkmcnt(4)
	v_cvt_pk_bf16_f32 v3, v12, v14
	s_mov_b64 s[0:1], 0
	s_waitcnt lgkmcnt(2)
	v_cvt_pk_bf16_f32 v4, v16, v18
	s_waitcnt lgkmcnt(0)
	v_cvt_pk_bf16_f32 v5, v20, v22
	global_store_dwordx4 v[24:25], v[2:5], off offset:128
	s_nop 1
	v_cvt_pk_bf16_f32 v2, v9, v11
	v_cvt_pk_bf16_f32 v3, v13, v15
	v_cvt_pk_bf16_f32 v4, v17, v19
	v_cvt_pk_bf16_f32 v5, v21, v23
	global_store_dwordx4 v[6:7], v[2:5], off offset:128
	s_barrier
.LBB0_777:
	s_andn2_b64 vcc, exec, s[0:1]
	s_cbranch_vccnz .LBB0_779
	s_lshl_b32 s0, s2, 1
	s_and_b32 s0, s0, 0x780
	v_mov_b32_e32 v10, v133
	s_add_i32 s10, s0, 0xfffffc80
	s_and_b32 s0, s3, 0xfc0
	s_lshl_b32 s1, s0, 2
	v_ashrrev_i32_e32 v8, 4, v10
	v_readlane_b32 s3, v207, 16
	v_add_u32_e32 v2, s10, v8
	s_add_u32 s4, s3, s1
	v_readlane_b32 s1, v207, 17
	v_lshlrev_b32_e32 v0, 4, v10
	s_addc_u32 s5, s1, 0
	v_and_b32_e32 v0, 0xf0, v0
	v_ashrrev_i32_e32 v3, 31, v2
	v_lshl_add_u64 v[4:5], s[4:5], 0, v[0:1]
	v_lshlrev_b64 v[2:3], 14, v[2:3]
	v_lshl_add_u64 v[6:7], v[4:5], 0, v[2:3]
	global_load_dwordx4 v[2:5], v[6:7], off sc1
	s_movk_i32 s1, 0x104
	v_mad_u64_u32 v[8:9], s[4:5], v8, s1, v[0:1]
	s_mov_b32 s3, 0x40000
	v_add_u32_e32 v0, 0x1040, v8
	s_lshl_b64 s[4:5], s[10:11], 1
	s_waitcnt vmcnt(0)
	ds_write2_b32 v8, v2, v3 offset1:1
	ds_write2_b32 v8, v4, v5 offset0:2 offset1:3
	v_add_co_u32_e32 v2, vcc, s3, v6
	s_mov_b32 s3, 0x80000
	s_nop 0
	v_addc_co_u32_e32 v3, vcc, 0, v7, vcc
	global_load_dwordx4 v[2:5], v[2:3], off sc1
	s_waitcnt vmcnt(0)
	ds_write2_b32 v0, v2, v3 offset1:1
	v_add_co_u32_e32 v2, vcc, s3, v6
	v_add_u32_e32 v0, 0x1048, v8
	s_nop 0
	v_addc_co_u32_e32 v3, vcc, 0, v7, vcc
	ds_write2_b32 v0, v4, v5 offset1:1
	global_load_dwordx4 v[2:5], v[2:3], off sc1
	v_add_u32_e32 v0, 0x2080, v8
	s_mov_b32 s3, 0xc0000
	s_waitcnt vmcnt(0)
	ds_write2_b32 v0, v2, v3 offset1:1
	v_add_co_u32_e32 v2, vcc, s3, v6
	v_add_u32_e32 v0, 0x2088, v8
	s_nop 0
	v_addc_co_u32_e32 v3, vcc, 0, v7, vcc
	ds_write2_b32 v0, v4, v5 offset1:1
	global_load_dwordx4 v[2:5], v[2:3], off sc1
	v_add_u32_e32 v0, 0x30c0, v8
	s_mov_b32 s3, 0x100000
	s_waitcnt vmcnt(0)
	ds_write2_b32 v0, v2, v3 offset1:1
	v_add_co_u32_e32 v2, vcc, s3, v6
	v_add_u32_e32 v0, 0x30c8, v8
	s_nop 0
	v_addc_co_u32_e32 v3, vcc, 0, v7, vcc
	ds_write2_b32 v0, v4, v5 offset1:1
	global_load_dwordx4 v[2:5], v[2:3], off sc1
	v_add_u32_e32 v0, 0x4100, v8
	s_mov_b32 s3, 0x140000
	s_waitcnt vmcnt(0)
	ds_write2_b32 v0, v2, v3 offset1:1
	v_add_co_u32_e32 v2, vcc, s3, v6
	v_add_u32_e32 v0, 0x4108, v8
	s_nop 0
	v_addc_co_u32_e32 v3, vcc, 0, v7, vcc
	ds_write2_b32 v0, v4, v5 offset1:1
	global_load_dwordx4 v[2:5], v[2:3], off sc1
	v_add_u32_e32 v0, 0x5140, v8
	s_mov_b32 s3, 0x180000
	s_waitcnt vmcnt(0)
	ds_write2_b32 v0, v2, v3 offset1:1
	v_add_co_u32_e32 v2, vcc, s3, v6
	v_add_u32_e32 v0, 0x5148, v8
	s_nop 0
	v_addc_co_u32_e32 v3, vcc, 0, v7, vcc
	ds_write2_b32 v0, v4, v5 offset1:1
	global_load_dwordx4 v[2:5], v[2:3], off sc1
	v_add_u32_e32 v0, 0x6180, v8
	s_mov_b32 s3, 0x1c0000
	s_waitcnt vmcnt(0)
	ds_write2_b32 v0, v2, v3 offset1:1
	v_add_co_u32_e32 v2, vcc, s3, v6
	v_add_u32_e32 v0, 0x6188, v8
	s_nop 0
	v_addc_co_u32_e32 v3, vcc, 0, v7, vcc
	ds_write2_b32 v0, v4, v5 offset1:1
	global_load_dwordx4 v[2:5], v[2:3], off sc1
	v_add_u32_e32 v0, 0x71c0, v8
	v_readlane_b32 s3, v207, 18
	s_add_u32 s4, s3, s4
	v_readlane_b32 s3, v207, 19
	s_addc_u32 s5, s3, s5
	s_waitcnt vmcnt(0)
	ds_write2_b32 v0, v2, v3 offset1:1
	v_add_u32_e32 v0, 0x71c8, v8
	ds_write2_b32 v0, v4, v5 offset1:1
	v_ashrrev_i32_e32 v0, 3, v10
	v_lshlrev_b32_e32 v2, 3, v10
	v_and_b32_e32 v26, 56, v2
	v_lshlrev_b32_e32 v27, 2, v0
	v_mad_u32_u24 v4, v26, s1, v27
	v_add_u32_e32 v5, 0x400, v4
	s_waitcnt lgkmcnt(0)
	s_barrier
	ds_read2_b32 v[6:7], v4 offset1:32
	ds_read2_b32 v[8:9], v4 offset0:65 offset1:97
	ds_read2_b32 v[10:11], v4 offset0:130 offset1:162
	ds_read2_b32 v[12:13], v4 offset0:195 offset1:227
	ds_read2_b32 v[14:15], v5 offset0:4 offset1:36
	ds_read2_b32 v[16:17], v5 offset0:69 offset1:101
	ds_read2_b32 v[18:19], v5 offset0:134 offset1:166
	ds_read2_b32 v[20:21], v5 offset0:199 offset1:231
	v_add_u32_e32 v22, s0, v0
	v_ashrrev_i32_e32 v23, 31, v22
	v_lshlrev_b64 v[24:25], 11, v[22:23]
	v_lshl_add_u64 v[24:25], s[4:5], 0, v[24:25]
	v_lshlrev_b32_e32 v0, 1, v26
	s_waitcnt lgkmcnt(6)
	v_cvt_pk_bf16_f32 v2, v6, v8
	s_waitcnt lgkmcnt(4)
	v_cvt_pk_bf16_f32 v3, v10, v12
	s_waitcnt lgkmcnt(2)
	v_cvt_pk_bf16_f32 v4, v14, v16
	s_waitcnt lgkmcnt(0)
	v_cvt_pk_bf16_f32 v5, v18, v20
	v_lshl_add_u64 v[24:25], v[24:25], 0, v[0:1]
	v_add_u32_e32 v6, 32, v22
	global_store_dwordx4 v[24:25], v[2:5], off
	s_nop 1
	v_cvt_pk_bf16_f32 v2, v7, v9
	v_ashrrev_i32_e32 v7, 31, v6
	v_lshlrev_b64 v[6:7], 11, v[6:7]
	v_lshl_add_u64 v[6:7], s[4:5], 0, v[6:7]
	v_cvt_pk_bf16_f32 v3, v11, v13
	v_cvt_pk_bf16_f32 v4, v15, v17
	v_cvt_pk_bf16_f32 v5, v19, v21
	v_lshl_add_u64 v[6:7], v[6:7], 0, v[0:1]
	v_or_b32_e32 v0, 64, v26
	global_store_dwordx4 v[6:7], v[2:5], off
	v_mad_u32_u24 v0, v0, s1, v27
	ds_read2_b32 v[8:9], v0 offset1:32
	ds_read2_b32 v[10:11], v0 offset0:65 offset1:97
	ds_read2_b32 v[12:13], v0 offset0:130 offset1:162
	ds_read2_b32 v[14:15], v0 offset0:195 offset1:227
	v_add_u32_e32 v0, 0x400, v0
	ds_read2_b32 v[16:17], v0 offset0:4 offset1:36
	ds_read2_b32 v[18:19], v0 offset0:69 offset1:101
	ds_read2_b32 v[20:21], v0 offset0:134 offset1:166
	ds_read2_b32 v[22:23], v0 offset0:199 offset1:231
	s_waitcnt lgkmcnt(6)
	v_cvt_pk_bf16_f32 v2, v8, v10
	s_waitcnt lgkmcnt(4)
	v_cvt_pk_bf16_f32 v3, v12, v14
	s_waitcnt lgkmcnt(2)
	v_cvt_pk_bf16_f32 v4, v16, v18
	s_waitcnt lgkmcnt(0)
	v_cvt_pk_bf16_f32 v5, v20, v22
	global_store_dwordx4 v[24:25], v[2:5], off offset:128
	s_nop 1
	v_cvt_pk_bf16_f32 v2, v9, v11
	v_cvt_pk_bf16_f32 v3, v13, v15
	v_cvt_pk_bf16_f32 v4, v17, v19
	v_cvt_pk_bf16_f32 v5, v21, v23
	global_store_dwordx4 v[6:7], v[2:5], off offset:128
	s_barrier

.LBB0_780:
	s_andn2_b64 vcc, exec, s[0:1]
	s_cbranch_vccnz .LBB0_782
	s_lshl_b32 s0, s2, 3
	s_and_b32 s0, s0, 0xf80
	s_add_i32 s10, s0, 0xfffff600
	s_lshl_b32 s0, s2, 6
	v_mov_b32_e32 v10, v133
	s_and_b32 s0, s0, 0x3c0
	s_lshl_b32 s1, s0, 2
	v_ashrrev_i32_e32 v8, 4, v10
	v_readlane_b32 s3, v207, 20
	v_add_u32_e32 v2, s10, v8
	s_add_u32 s4, s3, s1
	v_readlane_b32 s1, v207, 21
	v_lshlrev_b32_e32 v0, 4, v10
	s_addc_u32 s5, s1, 0
	v_and_b32_e32 v0, 0xf0, v0
	v_ashrrev_i32_e32 v3, 31, v2
	v_lshl_add_u64 v[4:5], s[4:5], 0, v[0:1]
	v_lshlrev_b64 v[2:3], 12, v[2:3]
	v_lshl_add_u64 v[6:7], v[4:5], 0, v[2:3]
	global_load_dwordx4 v[2:5], v[6:7], off sc1
	s_movk_i32 s1, 0x104
	v_mad_u64_u32 v[8:9], s[4:5], v8, s1, v[0:1]
	v_add_u32_e32 v0, 0x1040, v8
	s_mov_b32 s3, 0x40000
	s_lshl_b64 s[4:5], s[10:11], 1
	s_waitcnt vmcnt(0)
	ds_write2_b32 v8, v2, v3 offset1:1
	ds_write2_b32 v8, v4, v5 offset0:2 offset1:3
	v_add_co_u32_e32 v2, vcc, s56, v6
	s_nop 1
	v_addc_co_u32_e32 v3, vcc, 0, v7, vcc
	global_load_dwordx4 v[2:5], v[2:3], off sc1
	s_waitcnt vmcnt(0)
	ds_write2_b32 v0, v2, v3 offset1:1
	v_add_co_u32_e32 v2, vcc, s57, v6
	v_add_u32_e32 v0, 0x1048, v8
	s_nop 0
	v_addc_co_u32_e32 v3, vcc, 0, v7, vcc
	ds_write2_b32 v0, v4, v5 offset1:1
	global_load_dwordx4 v[2:5], v[2:3], off sc1
	v_add_u32_e32 v0, 0x2080, v8
	s_waitcnt vmcnt(0)
	ds_write2_b32 v0, v2, v3 offset1:1
	v_add_co_u32_e32 v2, vcc, s58, v6
	v_add_u32_e32 v0, 0x2088, v8
	s_nop 0
	v_addc_co_u32_e32 v3, vcc, 0, v7, vcc
	ds_write2_b32 v0, v4, v5 offset1:1
	global_load_dwordx4 v[2:5], v[2:3], off sc1
	v_add_u32_e32 v0, 0x30c0, v8
	s_waitcnt vmcnt(0)
	ds_write2_b32 v0, v2, v3 offset1:1
	v_add_co_u32_e32 v2, vcc, s3, v6
	v_add_u32_e32 v0, 0x30c8, v8
	s_nop 0
	v_addc_co_u32_e32 v3, vcc, 0, v7, vcc
	ds_write2_b32 v0, v4, v5 offset1:1
	global_load_dwordx4 v[2:5], v[2:3], off sc1
	v_add_u32_e32 v0, 0x4100, v8
	s_mov_b32 s3, 0x50000
	s_waitcnt vmcnt(0)
	ds_write2_b32 v0, v2, v3 offset1:1
	v_add_co_u32_e32 v2, vcc, s3, v6
	v_add_u32_e32 v0, 0x4108, v8
	s_nop 0
	v_addc_co_u32_e32 v3, vcc, 0, v7, vcc
	ds_write2_b32 v0, v4, v5 offset1:1
	global_load_dwordx4 v[2:5], v[2:3], off sc1
	v_add_u32_e32 v0, 0x5140, v8
	s_mov_b32 s3, 0x60000
	s_waitcnt vmcnt(0)
	ds_write2_b32 v0, v2, v3 offset1:1
	v_add_co_u32_e32 v2, vcc, s3, v6
	v_add_u32_e32 v0, 0x5148, v8
	s_nop 0
	v_addc_co_u32_e32 v3, vcc, 0, v7, vcc
	ds_write2_b32 v0, v4, v5 offset1:1
	global_load_dwordx4 v[2:5], v[2:3], off sc1
	v_add_u32_e32 v0, 0x6180, v8
	s_mov_b32 s3, 0x70000
	s_waitcnt vmcnt(0)
	ds_write2_b32 v0, v2, v3 offset1:1
	v_add_co_u32_e32 v2, vcc, s3, v6
	v_add_u32_e32 v0, 0x6188, v8
	s_nop 0
	v_addc_co_u32_e32 v3, vcc, 0, v7, vcc
	ds_write2_b32 v0, v4, v5 offset1:1
	global_load_dwordx4 v[2:5], v[2:3], off sc1
	v_add_u32_e32 v0, 0x71c0, v8
	v_readlane_b32 s3, v207, 22
	s_add_u32 s4, s3, s4
	v_readlane_b32 s3, v207, 23
	s_addc_u32 s5, s3, s5
	s_waitcnt vmcnt(0)
	ds_write2_b32 v0, v2, v3 offset1:1
	v_add_u32_e32 v0, 0x71c8, v8
	ds_write2_b32 v0, v4, v5 offset1:1
	v_ashrrev_i32_e32 v0, 3, v10
	v_lshlrev_b32_e32 v2, 3, v10
	v_and_b32_e32 v26, 56, v2
	v_lshlrev_b32_e32 v27, 2, v0
	v_mad_u32_u24 v4, v26, s1, v27
	v_add_u32_e32 v5, 0x400, v4
	s_waitcnt lgkmcnt(0)
	s_barrier
	ds_read2_b32 v[6:7], v4 offset1:32
	ds_read2_b32 v[8:9], v4 offset0:65 offset1:97
	ds_read2_b32 v[10:11], v4 offset0:130 offset1:162
	ds_read2_b32 v[12:13], v4 offset0:195 offset1:227
	ds_read2_b32 v[14:15], v5 offset0:4 offset1:36
	ds_read2_b32 v[16:17], v5 offset0:69 offset1:101
	ds_read2_b32 v[18:19], v5 offset0:134 offset1:166
	ds_read2_b32 v[20:21], v5 offset0:199 offset1:231
	v_add_u32_e32 v22, s0, v0
	v_ashrrev_i32_e32 v23, 31, v22
	v_lshlrev_b64 v[24:25], 11, v[22:23]
	v_lshl_add_u64 v[24:25], s[4:5], 0, v[24:25]
	v_lshlrev_b32_e32 v0, 1, v26
	s_waitcnt lgkmcnt(6)
	v_cvt_pk_bf16_f32 v2, v6, v8
	s_waitcnt lgkmcnt(4)
	v_cvt_pk_bf16_f32 v3, v10, v12
	s_waitcnt lgkmcnt(2)
	v_cvt_pk_bf16_f32 v4, v14, v16
	s_waitcnt lgkmcnt(0)
	v_cvt_pk_bf16_f32 v5, v18, v20
	v_lshl_add_u64 v[24:25], v[24:25], 0, v[0:1]
	v_add_u32_e32 v6, 32, v22
	global_store_dwordx4 v[24:25], v[2:5], off
	s_nop 1
	v_cvt_pk_bf16_f32 v2, v7, v9
	v_ashrrev_i32_e32 v7, 31, v6
	v_lshlrev_b64 v[6:7], 11, v[6:7]
	v_lshl_add_u64 v[6:7], s[4:5], 0, v[6:7]
	v_cvt_pk_bf16_f32 v3, v11, v13
	v_cvt_pk_bf16_f32 v4, v15, v17
	v_cvt_pk_bf16_f32 v5, v19, v21
	v_lshl_add_u64 v[6:7], v[6:7], 0, v[0:1]
	v_or_b32_e32 v0, 64, v26
	global_store_dwordx4 v[6:7], v[2:5], off
	v_mad_u32_u24 v0, v0, s1, v27
	ds_read2_b32 v[8:9], v0 offset1:32
	ds_read2_b32 v[10:11], v0 offset0:65 offset1:97
	ds_read2_b32 v[12:13], v0 offset0:130 offset1:162
	ds_read2_b32 v[14:15], v0 offset0:195 offset1:227
	v_add_u32_e32 v0, 0x400, v0
	ds_read2_b32 v[16:17], v0 offset0:4 offset1:36
	ds_read2_b32 v[18:19], v0 offset0:69 offset1:101
	ds_read2_b32 v[20:21], v0 offset0:134 offset1:166
	ds_read2_b32 v[22:23], v0 offset0:199 offset1:231
	s_waitcnt lgkmcnt(6)
	v_cvt_pk_bf16_f32 v2, v8, v10
	s_waitcnt lgkmcnt(4)
	v_cvt_pk_bf16_f32 v3, v12, v14
	s_waitcnt lgkmcnt(2)
	v_cvt_pk_bf16_f32 v4, v16, v18
	s_waitcnt lgkmcnt(0)
	v_cvt_pk_bf16_f32 v5, v20, v22
	global_store_dwordx4 v[24:25], v[2:5], off offset:128
	s_nop 1
	v_cvt_pk_bf16_f32 v2, v9, v11
	v_cvt_pk_bf16_f32 v3, v13, v15
	v_cvt_pk_bf16_f32 v4, v17, v19
	v_cvt_pk_bf16_f32 v5, v21, v23
	global_store_dwordx4 v[6:7], v[2:5], off offset:128
	s_barrier

.LBB0_783:
	s_andn2_b64 vcc, exec, s[0:1]
	s_cbranch_vccnz .LBB0_801
	s_and_b32 s0, s2, 0xffff
	s_mul_i32 s0, s0, 0xcccd
	s_lshr_b32 s0, s0, 21
	s_mul_i32 s1, s0, 40
	s_sub_i32 s3, s2, s1
	s_lshl_b32 s2, s0, 7
	s_and_b32 s6, s2, 0xff80
	s_and_b32 s7, s3, 0xffff
	s_cmp_lt_u32 s7, 39
	v_mov_b32_e32 v36, v133
	s_cselect_b64 s[0:1], -1, 0
	s_lshl_b32 s4, s3, 8
	s_and_b32 s4, s4, 0x3ff00
	v_lshlrev_b32_e32 v0, 2, v36
	v_readlane_b32 s5, v207, 24
	v_and_b32_e32 v37, 60, v0
	s_add_u32 s4, s5, s4
	v_readlane_b32 s5, v207, 25
	s_addc_u32 s5, s5, 0
	v_ashrrev_i32_e32 v38, 4, v36
	v_lshlrev_b32_e32 v0, 2, v37
	s_cmp_gt_u32 s7, 38
	v_add_u32_e32 v39, s6, v38
	v_lshl_add_u64 v[34:35], s[4:5], 0, v[0:1]
	v_mov_b32_e32 v2, 0
	v_mov_b32_e32 v6, 0
	v_mov_b32_e32 v7, 0
	v_mov_b32_e32 v8, 0
	v_mov_b32_e32 v9, 0
	s_cbranch_scc1 .LBB0_786
	s_movk_i32 s4, 0x2700
	v_mad_i64_i32 v[4:5], s[4:5], v39, s4, v[34:35]
	global_load_dwordx4 v[6:9], v[4:5], off sc1
.LBB0_786:
	v_cndmask_b32_e64 v0, 0, 1, s[0:1]
	v_cmp_ne_u32_e64 s[40:41], 1, v0
	s_andn2_b64 vcc, exec, s[0:1]
	v_mov_b32_e32 v3, 0
	v_mov_b32_e32 v4, 0
	v_mov_b32_e32 v5, 0
	s_cbranch_vccnz .LBB0_788
	v_add_u32_e32 v0, 16, v39
	s_movk_i32 s0, 0x2700
	v_mad_i64_i32 v[2:3], s[0:1], v0, s0, v[34:35]
	global_load_dwordx4 v[2:5], v[2:3], off sc1
.LBB0_788:
	v_mov_b32_e32 v10, 0
	s_and_b64 vcc, exec, s[40:41]
	v_mov_b32_e32 v14, 0
	v_mov_b32_e32 v15, 0
	v_mov_b32_e32 v16, 0
	v_mov_b32_e32 v17, 0
	s_cbranch_vccnz .LBB0_790
	v_add_u32_e32 v0, 32, v39
	s_movk_i32 s0, 0x2700
	v_mad_i64_i32 v[12:13], s[0:1], v0, s0, v[34:35]
	global_load_dwordx4 v[14:17], v[12:13], off sc1
.LBB0_790:
	s_and_b64 vcc, exec, s[40:41]
	v_mov_b32_e32 v11, 0
	v_mov_b32_e32 v12, 0
	v_mov_b32_e32 v13, 0
	s_cbranch_vccnz .LBB0_792
	v_add_u32_e32 v0, 48, v39
	s_movk_i32 s0, 0x2700
	v_mad_i64_i32 v[10:11], s[0:1], v0, s0, v[34:35]
	global_load_dwordx4 v[10:13], v[10:11], off sc1
.LBB0_792:
	v_mov_b32_e32 v18, 0
	s_and_b64 vcc, exec, s[40:41]
	v_mov_b32_e32 v22, 0
	v_mov_b32_e32 v23, 0
	v_mov_b32_e32 v24, 0
	v_mov_b32_e32 v25, 0
	s_cbranch_vccnz .LBB0_794
	v_add_u32_e32 v0, 64, v39
	s_movk_i32 s0, 0x2700
	v_mad_i64_i32 v[20:21], s[0:1], v0, s0, v[34:35]
	global_load_dwordx4 v[22:25], v[20:21], off sc1
.LBB0_794:
	s_and_b64 vcc, exec, s[40:41]
	v_mov_b32_e32 v19, 0
	v_mov_b32_e32 v20, 0
	v_mov_b32_e32 v21, 0
	s_cbranch_vccnz .LBB0_796
	v_add_u32_e32 v0, 0x50, v39
	s_movk_i32 s0, 0x2700
	v_mad_i64_i32 v[18:19], s[0:1], v0, s0, v[34:35]
	global_load_dwordx4 v[18:21], v[18:19], off sc1
.LBB0_796:
	v_mov_b32_e32 v26, 0
	s_and_b64 vcc, exec, s[40:41]
	v_mov_b32_e32 v30, 0
	v_mov_b32_e32 v31, 0
	v_mov_b32_e32 v32, 0
	v_mov_b32_e32 v33, 0
	s_cbranch_vccnz .LBB0_798
	v_add_u32_e32 v0, 0x60, v39
	s_movk_i32 s0, 0x2700
	v_mad_i64_i32 v[28:29], s[0:1], v0, s0, v[34:35]
	global_load_dwordx4 v[30:33], v[28:29], off sc1
.LBB0_798:
	s_and_b64 vcc, exec, s[40:41]
	v_mov_b32_e32 v27, 0
	v_mov_b32_e32 v28, 0
	v_mov_b32_e32 v29, 0
	s_cbranch_vccnz .LBB0_800
	v_add_u32_e32 v0, 0x70, v39
	s_movk_i32 s0, 0x2700
	v_mad_i64_i32 v[26:27], s[0:1], v0, s0, v[34:35]
	global_load_dwordx4 v[26:29], v[26:27], off sc1

.LBB0_807:
	v_ashrrev_i32_e32 v4, 5, v3
	v_add_u32_e32 v0, s34, v4
	v_cmp_lt_i32_e32 vcc, -1, v0
	v_cmp_gt_i32_e64 s[0:1], s7, v0
	s_and_b64 s[38:39], vcc, s[0:1]
	s_and_saveexec_b64 s[0:1], s[38:39]
	s_cbranch_execz .LBB0_806
	v_readlane_b32 s36, v210, 50
	v_readlane_b32 s48, v210, 62
	v_readlane_b32 s49, v210, 63
	v_add_u32_e32 v0, s10, v0
	v_readlane_b32 s38, v210, 52
	v_readlane_b32 s39, v210, 53
	v_mov_b64_e32 v[6:7], s[48:49]
	v_mad_u64_u32 v[6:7], s[38:39], v0, s68, v[6:7]
	v_lshlrev_b32_e32 v0, 1, v2
	v_and_b32_e32 v0, 0x1f0, v0
	v_lshl_add_u64 v[6:7], v[6:7], 0, v[0:1]
	v_lshl_or_b32 v0, v4, 9, v0
	global_load_dwordx4 v[4:7], v[6:7], off offset:2560 sc1
	v_readlane_b32 s37, v210, 51
	v_readlane_b32 s40, v210, 54
	v_readlane_b32 s41, v210, 55
	v_readlane_b32 s42, v210, 56
	v_readlane_b32 s43, v210, 57
	v_readlane_b32 s44, v210, 58
	v_readlane_b32 s45, v210, 59
	v_readlane_b32 s46, v210, 60
	v_readlane_b32 s47, v210, 61
	v_readlane_b32 s50, v209, 0
	v_readlane_b32 s51, v209, 1
	s_waitcnt vmcnt(0)
	ds_write_b128 v0, v[4:7]
	s_branch .LBB0_806

.LBB0_820:
	s_andn2_b64 vcc, exec, s[0:1]
	s_cbranch_vccnz .LBB0_770
	s_cmpk_gt_i32 s9, 0x3ff
	v_readlane_b32 s2, v207, 0
	s_cselect_b64 s[0:1], -1, 0
	v_readlane_b32 s3, v207, 1
	s_and_b64 s[0:1], s[2:3], s[0:1]
	s_and_b64 vcc, exec, s[0:1]
	s_cbranch_vccnz .LBB0_770
	s_bfe_u32 s37, s9, 0x20005
	s_cmpk_gt_i32 s9, 0x1ff
	s_mov_b64 s[0:1], -1
	s_cbranch_scc0 .LBB0_1019
	s_cmpk_gt_u32 s9, 0x3ff
	s_cbranch_scc0 .LBB0_841
	s_lshl_b32 s0, s9, 7
	s_bfe_u32 s2, s9, 0x20001
	s_and_b32 s10, s0, 0x80
	s_cmpk_gt_u32 s9, 0x41f
	s_mov_b64 s[0:1], -1
	s_cbranch_scc0 .LBB0_832
	s_add_i32 s0, s9, 0xfffffbe0
	s_lshr_b32 s3, s0, 3
	s_lshl_b32 s0, s3, 2
	s_or_b32 s6, s0, s2
	s_mul_hi_u32 s1, s6, 0x1100
	s_mul_i32 s0, s6, 0x1100
	s_or_b64 s[0:1], s[0:1], s[10:11]
	s_lshl_b64 s[0:1], s[0:1], 7
	s_add_u32 s4, s72, s0
	s_addc_u32 s5, s73, s1
	s_mul_hi_u32 s7, s6, 0x88000
	s_mul_i32 s6, s6, 0x88000
	v_mov_b32_e32 v28, v133
	s_add_u32 s0, s74, s6
	s_movk_i32 s34, 0xffe0
	v_ashrrev_i32_e32 v30, 1, v28
	s_addc_u32 s1, s75, s7
	v_bfi_b32 v2, s34, v30, v28
	s_add_u32 s6, s76, s6
	v_ashrrev_i32_e32 v3, 31, v2
	v_ashrrev_i32_e32 v20, 2, v28
	s_addc_u32 s7, s77, s7
	v_bfe_u32 v29, v28, 5, 1
	v_lshlrev_b64 v[2:3], 7, v[2:3]
	v_ashrrev_i32_e32 v21, 31, v20
	v_lshl_add_u64 v[2:3], s[4:5], 0, v[2:3]
	v_lshlrev_b32_e32 v0, 4, v29
	v_and_b32_e32 v26, 3, v28
	v_lshlrev_b64 v[22:23], 7, v[20:21]
	v_mov_b64_e32 v[10:11], s[6:7]
	v_lshl_add_u64 v[18:19], v[2:3], 0, v[0:1]
	v_lshl_add_u64 v[2:3], s[0:1], 0, v[22:23]
	v_lshlrev_b32_e32 v0, 5, v26
	v_mad_i64_i32 v[10:11], s[4:5], v20, s52, v[10:11]
	v_lshl_add_u64 v[24:25], v[2:3], 0, v[0:1]
	s_waitcnt vmcnt(9)
	v_lshl_add_u64 v[114:115], v[10:11], 0, v[0:1]
	global_load_dwordx4 v[2:5], v[24:25], off offset:16 sc1
	global_load_dwordx4 v[6:9], v[24:25], off sc1
	global_load_dwordx4 v[10:13], v[114:115], off sc1
	global_load_dwordx4 v[14:17], v[114:115], off offset:16 sc1
	s_waitcnt vmcnt(12)
	v_lshlrev_b32_e32 v117, 7, v20
	v_bfe_u32 v21, v20, 1, 3
	v_lshlrev_b32_e32 v26, 1, v26
	v_lshl_add_u32 v20, v20, 3, v117
	s_mov_b64 s[4:5], 0x2000
	v_lshlrev_b32_e32 v31, 4, v21
	v_bitop3_b32 v21, v26, v21, 1 bitop3:0x36
	global_load_dwordx4 v[66:69], v[18:19], off sc1
	global_load_dwordx4 v[70:73], v[18:19], off offset:32 sc1
	global_load_dwordx4 v[74:77], v[18:19], off offset:64 sc1
	global_load_dwordx4 v[78:81], v[18:19], off offset:96 sc1
	v_add_u32_e32 v121, v20, v0
	v_lshl_add_u64 v[18:19], v[24:25], 0, s[4:5]
	v_add_co_u32_e32 v20, vcc, s53, v24
	s_mov_b64 s[4:5], 0x4000
	v_lshlrev_b32_e32 v120, 4, v21
	v_addc_co_u32_e32 v21, vcc, 0, v25, vcc
	v_lshl_add_u64 v[26:27], v[24:25], 0, s[4:5]
	s_movk_i32 s4, 0x4000
	v_add_co_u32_e32 v24, vcc, s4, v24
	v_bitop3_b32 v33, v117, v31, v0 bitop3:0xf6
	s_nop 0
	v_addc_co_u32_e32 v25, vcc, 0, v25, vcc
	v_or_b32_e32 v32, v117, v120
	v_add_u32_e32 v122, 0x4000, v121
	v_add_u32_e32 v123, 0x4010, v121
	global_load_dwordx4 v[82:85], v[20:21], off sc1
	global_load_dwordx4 v[86:89], v[18:19], off offset:16 sc1
	global_load_dwordx4 v[98:101], v[114:115], off offset:144 sc1
	global_load_dwordx4 v[102:105], v[114:115], off offset:128 sc1
	v_and_b32_e32 v124, 31, v28
	v_lshlrev_b32_e32 v116, 3, v29
	v_mov_b32_e32 v137, 0
	v_and_b32_e32 v125, 0xffffffe0, v30
	v_mov_b32_e32 v181, 0xff800000
	s_mov_b64 s[34:35], -1
	v_mov_b32_e32 v18, 0
	v_mov_b32_e32 v19, v137
	v_mov_b32_e32 v20, v137
	v_mov_b32_e32 v21, v137
	v_mov_b32_e32 v30, v137
	s_waitcnt vmcnt(10)
	ds_write_b128 v33, v[6:9]
	ds_write_b128 v32, v[2:5]
	s_waitcnt vmcnt(9)
	ds_write2_b64 v122, v[10:11], v[12:13] offset1:1
	s_waitcnt vmcnt(8)
	ds_write2_b64 v123, v[14:15], v[16:17] offset1:1
	s_waitcnt lgkmcnt(0)
	s_barrier
	global_load_dwordx4 v[90:93], v[24:25], off sc1
	global_load_dwordx4 v[94:97], v[26:27], off offset:16 sc1
	global_load_dwordx4 v[106:109], v[114:115], off offset:272 sc1
	global_load_dwordx4 v[110:113], v[114:115], off offset:256 sc1
	v_lshrrev_b32_e32 v2, 5, v28
	v_bfe_u32 v3, v28, 1, 3
	v_bitop3_b32 v2, v2, v3, 1 bitop3:0x6c
	v_lshlrev_b32_e32 v6, 4, v2
	v_bitop3_b32 v2, v29, v3, 2 bitop3:0x36
	v_lshlrev_b32_e32 v7, 4, v2
	v_bitop3_b32 v2, v29, v3, 4 bitop3:0x36
	v_lshlrev_b32_e32 v8, 4, v2
	v_bitop3_b32 v2, v29, v3, 6 bitop3:0x36
	v_and_b32_e32 v3, 64, v179
	v_lshlrev_b32_e32 v9, 4, v2
	v_xor_b32_e32 v2, 32, v179
	v_add_u32_e32 v3, 64, v3
	v_cmp_lt_i32_e32 vcc, v2, v3
	v_lshlrev_b32_e32 v5, 7, v124
	v_xor_b32_e32 v4, v31, v0
	v_cndmask_b32_e32 v2, v179, v2, vcc
	v_lshlrev_b32_e32 v126, 2, v2
	v_lshl_add_u64 v[2:3], s[0:1], 0, v[0:1]
	v_lshl_add_u32 v10, v124, 3, v5
	v_lshl_add_u64 v[2:3], v[2:3], 0, v[22:23]
	s_mov_b64 s[0:1], 0x6000
	v_lshl_add_u64 v[118:119], v[2:3], 0, s[0:1]
	v_add_u32_e32 v127, v5, v6
	v_add_u32_e32 v128, v5, v7
	v_add_u32_e32 v129, v5, v8
	v_add_u32_e32 v134, v5, v9
	v_add_u32_e32 v135, v10, v116
	v_add_u32_e32 v136, v117, v4
	v_mov_b32_e32 v2, 0
	v_mov_b32_e32 v3, v137
	v_mov_b32_e32 v4, v137
	v_mov_b32_e32 v5, v137
	v_mov_b32_e32 v6, v137
	v_mov_b32_e32 v7, v137
	v_mov_b32_e32 v8, v137
	v_mov_b32_e32 v9, v137
	v_mov_b32_e32 v10, v137
	v_mov_b32_e32 v11, v137
	v_mov_b32_e32 v12, v137
	v_mov_b32_e32 v13, v137
	v_mov_b32_e32 v14, v137
	v_mov_b32_e32 v15, v137
	v_mov_b32_e32 v16, v137
	v_mov_b32_e32 v17, v137
	v_mov_b32_e32 v22, v137
	v_mov_b32_e32 v23, v137
	v_mov_b32_e32 v24, v137
	v_mov_b32_e32 v25, v137
	v_mov_b32_e32 v26, v137
	v_mov_b32_e32 v27, v137
	v_mov_b32_e32 v28, v137
	v_mov_b32_e32 v29, v137
	v_mov_b32_e32 v31, v137
	v_mov_b32_e32 v32, v137
	v_mov_b32_e32 v33, v137
	s_branch .LBB0_827

.LBB0_827:
	s_xor_b64 s[0:1], s[34:35], -1
	v_add_u32_e32 v182, v117, v120
	s_and_b64 vcc, exec, s[0:1]
	ds_read_b128 v[34:37], v127
	ds_read_b128 v[212:215], v128
	ds_read_b128 v[216:219], v129
	ds_read_b128 v[220:223], v134
	ds_read_b128 v[224:227], v127 offset:4096
	ds_read_b128 v[138:141], v128 offset:4096
	ds_read_b128 v[228:231], v129 offset:4096
	ds_read_b128 v[232:235], v134 offset:4096
	s_waitcnt vmcnt(11) lgkmcnt(7)
	s_nop 0
	v_mfma_f32_32x32x16_bf16 v[50:65], v[34:37], v[66:69], 0
	s_waitcnt vmcnt(10) lgkmcnt(6)
	s_nop 0
	v_mfma_f32_32x32x16_bf16 v[50:65], v[212:215], v[70:73], v[50:65]
	s_waitcnt vmcnt(9) lgkmcnt(5)
	s_nop 0
	v_mfma_f32_32x32x16_bf16 v[50:65], v[216:219], v[74:77], v[50:65]
	s_waitcnt vmcnt(8) lgkmcnt(4)
	s_nop 0
	v_mfma_f32_32x32x16_bf16 v[50:65], v[220:223], v[78:81], v[50:65]
	s_waitcnt lgkmcnt(3)
	s_nop 0
	v_mfma_f32_32x32x16_bf16 v[34:49], v[224:227], v[66:69], 0
	s_nop 8
	v_max_f32_e32 v0, v51, v51
	s_waitcnt lgkmcnt(2)
	s_nop 0
	v_mfma_f32_32x32x16_bf16 v[34:49], v[138:141], v[70:73], v[34:49]
	s_waitcnt lgkmcnt(1)
	s_nop 0
	v_mfma_f32_32x32x16_bf16 v[34:49], v[228:231], v[74:77], v[34:49]
	s_waitcnt lgkmcnt(0)
	s_nop 0
	v_mfma_f32_32x32x16_bf16 v[34:49], v[232:235], v[78:81], v[34:49]
	v_max_f32_e32 v138, v50, v50
	v_max_f32_e32 v0, v138, v0
	v_max3_f32 v0, v0, v52, v53
	v_max3_f32 v0, v0, v54, v55
	v_max3_f32 v0, v0, v56, v57
	v_max3_f32 v0, v0, v58, v59
	v_max3_f32 v0, v0, v60, v61
	v_max3_f32 v0, v0, v62, v63
	v_max3_f32 v0, v0, v64, v65
	s_nop 2
	v_max3_f32 v0, v0, v34, v35
	v_max3_f32 v0, v0, v36, v37
	v_max3_f32 v0, v0, v38, v39
	v_max3_f32 v0, v0, v40, v41
	v_max3_f32 v0, v0, v42, v43
	v_max3_f32 v0, v0, v44, v45
	v_max3_f32 v0, v0, v46, v47
	v_max3_f32 v0, v0, v48, v49
	ds_bpermute_b32 v138, v126, v0
	s_waitcnt lgkmcnt(0)
	v_max3_f32 v183, v181, v0, v138
	v_sub_f32_e32 v34, v34, v183
	v_exp_f32_e32 v154, v34
	v_sub_f32_e32 v34, v35, v183
	v_exp_f32_e32 v155, v34
	v_sub_f32_e32 v34, v36, v183
	v_exp_f32_e32 v156, v34
	v_sub_f32_e32 v34, v37, v183
	v_sub_f32_e32 v50, v50, v183
	v_exp_f32_e32 v157, v34
	v_sub_f32_e32 v34, v38, v183
	v_exp_f32_e32 v138, v50
	v_sub_f32_e32 v50, v51, v183
	v_exp_f32_e32 v158, v34
	v_sub_f32_e32 v34, v39, v183
	v_exp_f32_e32 v139, v50
	v_sub_f32_e32 v50, v52, v183
	v_exp_f32_e32 v159, v34
	v_sub_f32_e32 v34, v40, v183
	v_exp_f32_e32 v140, v50
	v_sub_f32_e32 v50, v53, v183
	v_exp_f32_e32 v160, v34
	v_sub_f32_e32 v34, v41, v183
	v_exp_f32_e32 v141, v50
	v_sub_f32_e32 v50, v54, v183
	v_exp_f32_e32 v161, v34
	v_sub_f32_e32 v34, v42, v183
	v_exp_f32_e32 v142, v50
	v_sub_f32_e32 v50, v55, v183
	v_exp_f32_e32 v162, v34
	v_sub_f32_e32 v34, v43, v183
	v_exp_f32_e32 v143, v50
	v_sub_f32_e32 v50, v56, v183
	v_exp_f32_e32 v163, v34
	v_sub_f32_e32 v34, v44, v183
	v_sub_f32_e32 v0, v181, v183
	v_exp_f32_e32 v144, v50
	v_sub_f32_e32 v50, v57, v183
	v_exp_f32_e32 v164, v34
	v_sub_f32_e32 v34, v45, v183
	v_exp_f32_e32 v145, v50
	v_exp_f32_e32 v165, v34
	v_sub_f32_e32 v34, v46, v183
	v_exp_f32_e32 v0, v0
	v_add_u32_e32 v46, 0x4000, v135
	v_exp_f32_e32 v166, v34
	v_sub_f32_e32 v34, v47, v183
	ds_read2_b64 v[38:41], v46 offset1:2
	ds_read2_b64 v[42:45], v46 offset0:4 offset1:6
	v_exp_f32_e32 v167, v34
	v_sub_f32_e32 v34, v48, v183
	v_exp_f32_e32 v168, v34
	v_sub_f32_e32 v34, v49, v183
	v_exp_f32_e32 v169, v34
	v_pk_mul_f32 v[32:33], v[32:33], v[0:1] op_sel_hi:[1,0]
	v_pk_mul_f32 v[30:31], v[30:31], v[0:1] op_sel_hi:[1,0]
	v_pk_mul_f32 v[28:29], v[28:29], v[0:1] op_sel_hi:[1,0]
	v_pk_mul_f32 v[26:27], v[26:27], v[0:1] op_sel_hi:[1,0]
	v_pk_mul_f32 v[24:25], v[24:25], v[0:1] op_sel_hi:[1,0]
	v_pk_mul_f32 v[22:23], v[22:23], v[0:1] op_sel_hi:[1,0]
	v_pk_mul_f32 v[20:21], v[20:21], v[0:1] op_sel_hi:[1,0]
	v_pk_mul_f32 v[18:19], v[18:19], v[0:1] op_sel_hi:[1,0]
	v_cvt_pk_bf16_f32 v34, v138, v139
	v_cvt_pk_bf16_f32 v35, v140, v141
	v_cvt_pk_bf16_f32 v36, v142, v143
	v_cvt_pk_bf16_f32 v37, v144, v145
	v_add_u32_e32 v47, 0x5000, v135
	v_sub_f32_e32 v50, v58, v183
	s_waitcnt lgkmcnt(1)
	v_mfma_f32_32x32x16_bf16 v[18:33], v[38:41], v[34:37], v[18:33]
	ds_read2_b64 v[38:41], v47 offset0:32 offset1:34
	v_exp_f32_e32 v146, v50
	v_sub_f32_e32 v50, v59, v183
	v_exp_f32_e32 v147, v50
	v_sub_f32_e32 v50, v60, v183
	v_exp_f32_e32 v148, v50
	v_sub_f32_e32 v50, v61, v183
	v_pk_mul_f32 v[16:17], v[16:17], v[0:1] op_sel_hi:[1,0]
	v_pk_mul_f32 v[14:15], v[14:15], v[0:1] op_sel_hi:[1,0]
	v_pk_mul_f32 v[12:13], v[12:13], v[0:1] op_sel_hi:[1,0]
	v_pk_mul_f32 v[10:11], v[10:11], v[0:1] op_sel_hi:[1,0]
	v_pk_mul_f32 v[8:9], v[8:9], v[0:1] op_sel_hi:[1,0]
	v_pk_mul_f32 v[6:7], v[6:7], v[0:1] op_sel_hi:[1,0]
	v_pk_mul_f32 v[4:5], v[4:5], v[0:1] op_sel_hi:[1,0]
	v_pk_mul_f32 v[2:3], v[2:3], v[0:1] op_sel_hi:[1,0]
	v_exp_f32_e32 v149, v50
	v_sub_f32_e32 v50, v62, v183
	s_waitcnt lgkmcnt(0)
	v_mfma_f32_32x32x16_bf16 v[2:17], v[38:41], v[34:37], v[2:17]
	ds_read2_b64 v[38:41], v47 offset0:36 offset1:38
	v_exp_f32_e32 v150, v50
	v_sub_f32_e32 v50, v63, v183
	v_exp_f32_e32 v151, v50
	v_sub_f32_e32 v50, v64, v183
	v_exp_f32_e32 v152, v50
	v_sub_f32_e32 v50, v65, v183
	v_exp_f32_e32 v153, v50
	v_cvt_pk_bf16_f32 v34, v146, v147
	v_cvt_pk_bf16_f32 v35, v148, v149
	v_cvt_pk_bf16_f32 v36, v150, v151
	v_cvt_pk_bf16_f32 v37, v152, v153
	s_waitcnt lgkmcnt(0)
	s_nop 0
	v_mfma_f32_32x32x16_bf16 v[2:17], v[38:41], v[34:37], v[2:17]
	ds_read2_b64 v[38:41], v46 offset0:8 offset1:10
	v_mfma_f32_32x32x16_bf16 v[18:33], v[42:45], v[34:37], v[18:33]
	v_cvt_pk_bf16_f32 v34, v154, v155
	v_cvt_pk_bf16_f32 v35, v156, v157
	v_cvt_pk_bf16_f32 v36, v158, v159
	v_cvt_pk_bf16_f32 v37, v160, v161
	s_waitcnt lgkmcnt(0)
	s_nop 0
	v_mfma_f32_32x32x16_bf16 v[18:33], v[38:41], v[34:37], v[18:33]
	ds_read2_b64 v[38:41], v47 offset0:40 offset1:42
	s_waitcnt lgkmcnt(0)
	v_mfma_f32_32x32x16_bf16 v[2:17], v[38:41], v[34:37], v[2:17]
	ds_read2_b64 v[38:41], v46 offset0:12 offset1:14
	v_cvt_pk_bf16_f32 v34, v162, v163
	v_cvt_pk_bf16_f32 v35, v164, v165
	v_cvt_pk_bf16_f32 v36, v166, v167
	v_cvt_pk_bf16_f32 v37, v168, v169
	s_waitcnt lgkmcnt(0)
	s_nop 0
	v_mfma_f32_32x32x16_bf16 v[18:33], v[38:41], v[34:37], v[18:33]
	ds_read2_b64 v[38:41], v47 offset0:44 offset1:46
	s_waitcnt vmcnt(2)
	ds_write_b128 v136, v[82:85] offset:8192
	s_waitcnt vmcnt(6)
	ds_write_b128 v182, v[86:89] offset:8192
	s_waitcnt lgkmcnt(2)
	v_mfma_f32_32x32x16_bf16 v[2:17], v[38:41], v[34:37], v[2:17]
	v_add_u32_e32 v34, 0x6200, v121
	s_waitcnt vmcnt(0)
	ds_write2_b64 v34, v[102:103], v[104:105] offset1:1
	v_add_u32_e32 v34, 0x6210, v121
	ds_write2_b64 v34, v[98:99], v[100:101] offset1:1
	s_waitcnt lgkmcnt(0)
	s_barrier
	s_cbranch_vccnz .LBB0_829
	global_load_dwordx4 v[86:89], v[118:119], off offset:16 sc1
	global_load_dwordx4 v[82:85], v[118:119], off sc1
	global_load_dwordx4 v[98:101], v[114:115], off offset:400 sc1
	global_load_dwordx4 v[102:105], v[114:115], off offset:384 sc1

.LBB0_832:
	s_and_b64 vcc, exec, s[0:1]
	s_cbranch_vccz .LBB0_840
	s_add_i32 s0, s9, 0xfffffc00
	s_lshr_b32 s3, s0, 3
	s_lshl_b32 s0, s3, 2
	s_or_b32 s0, s0, s2
	s_mul_hi_u32 s1, s0, 0x1100
	s_mulk_i32 s0, 0x1100
	s_or_b64 s[0:1], s[0:1], s[10:11]
	s_lshl_b64 s[0:1], s[0:1], 7
	s_add_u32 s4, s78, s0
	s_addc_u32 s5, s79, s1
	s_lshl_b32 s0, s3, 1
	s_lshr_b32 s1, s2, 1
	s_or_b32 s0, s0, s1
	s_mul_i32 s6, s0, 0x88000
	v_mov_b32_e32 v28, v133
	s_mul_hi_u32 s7, s0, 0x88000
	s_add_u32 s0, s60, s6
	s_movk_i32 s34, 0xffe0
	v_ashrrev_i32_e32 v30, 1, v28
	s_addc_u32 s1, s61, s7
	v_bfi_b32 v2, s34, v30, v28
	s_add_u32 s6, s62, s6
	v_ashrrev_i32_e32 v3, 31, v2
	v_ashrrev_i32_e32 v20, 2, v28
	s_addc_u32 s7, s63, s7
	v_bfe_u32 v29, v28, 5, 1
	v_lshlrev_b64 v[2:3], 7, v[2:3]
	v_ashrrev_i32_e32 v21, 31, v20
	v_lshl_add_u64 v[2:3], s[4:5], 0, v[2:3]
	v_lshlrev_b32_e32 v0, 4, v29
	v_and_b32_e32 v26, 3, v28
	v_lshlrev_b64 v[22:23], 7, v[20:21]
	v_mov_b64_e32 v[10:11], s[6:7]
	v_lshl_add_u64 v[18:19], v[2:3], 0, v[0:1]
	v_lshl_add_u64 v[2:3], s[0:1], 0, v[22:23]
	v_lshlrev_b32_e32 v0, 5, v26
	v_mad_i64_i32 v[10:11], s[4:5], v20, s52, v[10:11]
	v_lshl_add_u64 v[24:25], v[2:3], 0, v[0:1]
	s_waitcnt vmcnt(9)
	v_lshl_add_u64 v[114:115], v[10:11], 0, v[0:1]
	global_load_dwordx4 v[2:5], v[24:25], off offset:16 sc1
	global_load_dwordx4 v[6:9], v[24:25], off sc1
	global_load_dwordx4 v[10:13], v[114:115], off sc1
	global_load_dwordx4 v[14:17], v[114:115], off offset:16 sc1
	s_waitcnt vmcnt(12)
	v_lshlrev_b32_e32 v117, 7, v20
	v_bfe_u32 v21, v20, 1, 3
	v_lshlrev_b32_e32 v26, 1, v26
	v_lshl_add_u32 v20, v20, 3, v117
	s_mov_b64 s[4:5], 0x2000
	v_lshlrev_b32_e32 v31, 4, v21
	v_bitop3_b32 v21, v26, v21, 1 bitop3:0x36
	global_load_dwordx4 v[66:69], v[18:19], off sc1
	global_load_dwordx4 v[70:73], v[18:19], off offset:32 sc1
	global_load_dwordx4 v[74:77], v[18:19], off offset:64 sc1
	global_load_dwordx4 v[78:81], v[18:19], off offset:96 sc1
	v_add_u32_e32 v121, v20, v0
	v_lshl_add_u64 v[18:19], v[24:25], 0, s[4:5]
	v_add_co_u32_e32 v20, vcc, s53, v24
	s_mov_b64 s[4:5], 0x4000
	v_lshlrev_b32_e32 v120, 4, v21
	v_addc_co_u32_e32 v21, vcc, 0, v25, vcc
	v_lshl_add_u64 v[26:27], v[24:25], 0, s[4:5]
	s_movk_i32 s4, 0x4000
	v_add_co_u32_e32 v24, vcc, s4, v24
	v_bitop3_b32 v33, v117, v31, v0 bitop3:0xf6
	s_nop 0
	v_addc_co_u32_e32 v25, vcc, 0, v25, vcc
	v_or_b32_e32 v32, v117, v120
	v_add_u32_e32 v122, 0x4000, v121
	v_add_u32_e32 v123, 0x4010, v121
	global_load_dwordx4 v[82:85], v[20:21], off sc1
	global_load_dwordx4 v[86:89], v[18:19], off offset:16 sc1
	global_load_dwordx4 v[98:101], v[114:115], off offset:144 sc1
	global_load_dwordx4 v[102:105], v[114:115], off offset:128 sc1
	v_and_b32_e32 v124, 31, v28
	v_lshlrev_b32_e32 v116, 3, v29
	v_mov_b32_e32 v137, 0
	v_and_b32_e32 v125, 0xffffffe0, v30
	v_mov_b32_e32 v181, 0xff800000
	s_mov_b64 s[34:35], -1
	v_mov_b32_e32 v18, 0
	v_mov_b32_e32 v19, v137
	v_mov_b32_e32 v20, v137
	v_mov_b32_e32 v21, v137
	v_mov_b32_e32 v30, v137
	s_waitcnt vmcnt(10)
	ds_write_b128 v33, v[6:9]
	ds_write_b128 v32, v[2:5]
	s_waitcnt vmcnt(9)
	ds_write2_b64 v122, v[10:11], v[12:13] offset1:1
	s_waitcnt vmcnt(8)
	ds_write2_b64 v123, v[14:15], v[16:17] offset1:1
	s_waitcnt lgkmcnt(0)
	s_barrier
	global_load_dwordx4 v[90:93], v[24:25], off sc1
	global_load_dwordx4 v[94:97], v[26:27], off offset:16 sc1
	global_load_dwordx4 v[106:109], v[114:115], off offset:272 sc1
	global_load_dwordx4 v[110:113], v[114:115], off offset:256 sc1
	v_lshrrev_b32_e32 v2, 5, v28
	v_bfe_u32 v3, v28, 1, 3
	v_bitop3_b32 v2, v2, v3, 1 bitop3:0x6c
	v_lshlrev_b32_e32 v6, 4, v2
	v_bitop3_b32 v2, v29, v3, 2 bitop3:0x36
	v_lshlrev_b32_e32 v7, 4, v2
	v_bitop3_b32 v2, v29, v3, 4 bitop3:0x36
	v_lshlrev_b32_e32 v8, 4, v2
	v_bitop3_b32 v2, v29, v3, 6 bitop3:0x36
	v_and_b32_e32 v3, 64, v179
	v_lshlrev_b32_e32 v9, 4, v2
	v_xor_b32_e32 v2, 32, v179
	v_add_u32_e32 v3, 64, v3
	v_cmp_lt_i32_e32 vcc, v2, v3
	v_lshlrev_b32_e32 v5, 7, v124
	v_xor_b32_e32 v4, v31, v0
	v_cndmask_b32_e32 v2, v179, v2, vcc
	v_lshlrev_b32_e32 v126, 2, v2
	v_lshl_add_u64 v[2:3], s[0:1], 0, v[0:1]
	v_lshl_add_u32 v10, v124, 3, v5
	v_lshl_add_u64 v[2:3], v[2:3], 0, v[22:23]
	s_mov_b64 s[0:1], 0x6000
	v_lshl_add_u64 v[118:119], v[2:3], 0, s[0:1]
	v_add_u32_e32 v127, v5, v6
	v_add_u32_e32 v128, v5, v7
	v_add_u32_e32 v129, v5, v8
	v_add_u32_e32 v134, v5, v9
	v_add_u32_e32 v135, v10, v116
	v_add_u32_e32 v136, v117, v4
	v_mov_b32_e32 v2, 0
	v_mov_b32_e32 v3, v137
	v_mov_b32_e32 v4, v137
	v_mov_b32_e32 v5, v137
	v_mov_b32_e32 v6, v137
	v_mov_b32_e32 v7, v137
	v_mov_b32_e32 v8, v137
	v_mov_b32_e32 v9, v137
	v_mov_b32_e32 v10, v137
	v_mov_b32_e32 v11, v137
	v_mov_b32_e32 v12, v137
	v_mov_b32_e32 v13, v137
	v_mov_b32_e32 v14, v137
	v_mov_b32_e32 v15, v137
	v_mov_b32_e32 v16, v137
	v_mov_b32_e32 v17, v137
	v_mov_b32_e32 v22, v137
	v_mov_b32_e32 v23, v137
	v_mov_b32_e32 v24, v137
	v_mov_b32_e32 v25, v137
	v_mov_b32_e32 v26, v137
	v_mov_b32_e32 v27, v137
	v_mov_b32_e32 v28, v137
	v_mov_b32_e32 v29, v137
	v_mov_b32_e32 v31, v137
	v_mov_b32_e32 v32, v137
	v_mov_b32_e32 v33, v137
	s_branch .LBB0_835

.LBB0_850:
	s_or_b64 exec, exec, s[0:1]
	s_add_i32 s0, s9, 0xfffffe00
	s_lshr_b32 s49, s0, 7
	s_and_b32 s4, s9, 31
	s_lshl_b32 s0, s49, 2
	s_or_b32 s5, s0, s37
	s_lshl_b32 s50, s4, 7
	s_mul_i32 s0, s5, 0x1100
	s_add_i32 s2, s50, 0x100
	s_mul_hi_u32 s1, s5, 0x1100
	s_add_u32 s0, s0, s2
	s_addc_u32 s1, s1, 0
	s_lshl_b64 s[0:1], s[0:1], 7
	s_add_u32 s2, s72, s0
	s_addc_u32 s3, s73, s1
	s_mul_hi_u32 s6, s5, 0x88000
	s_mul_i32 s5, s5, 0x88000
	s_add_u32 s0, s74, s5
	s_addc_u32 s1, s75, s6
	s_add_u32 s34, s76, s5
	s_addc_u32 s35, s77, s6
	s_lshl_b32 s4, s4, 1
	v_sub_u32_e64 v0, s4, 4 clamp
	v_ashrrev_i32_e32 v129, 1, v2
	v_readfirstlane_b32 s5, v0
	v_sub_u32_e64 v0, s4, 3 clamp
	s_min_u32 s10, s5, 56
	v_readfirstlane_b32 s5, v0
	s_min_u32 s5, s5, 56
	s_sub_i32 s6, s5, s10
	s_movk_i32 s5, 0xffe0
	v_bfi_b32 v4, s5, v129, v2
	v_ashrrev_i32_e32 v5, 31, v4
	s_add_i32 s6, s6, 8
	v_lshlrev_b64 v[4:5], 7, v[4:5]
	v_lshl_add_u64 v[4:5], s[2:3], 0, v[4:5]
	s_lshl_b32 s2, s10, 6
	s_lshl_b32 s3, s6, 6
	v_bfe_u32 v3, v2, 5, 1
	s_add_i32 s5, s2, 0x100
	s_sub_i32 s7, 0, s3
	v_lshlrev_b32_e32 v0, 4, v3
	s_cmp_gt_i32 s6, 0
	v_lshl_add_u64 v[4:5], v[4:5], 0, v[0:1]
	v_ashrrev_i32_e32 v138, 2, v2
	s_cselect_b32 s38, s5, s7
	global_load_dwordx4 v[80:83], v[4:5], off sc1
	global_load_dwordx4 v[84:87], v[4:5], off offset:32 sc1
	global_load_dwordx4 v[88:91], v[4:5], off offset:64 sc1
	global_load_dwordx4 v[92:95], v[4:5], off offset:96 sc1
	v_add_u32_e32 v4, s38, v138
	v_ashrrev_i32_e32 v5, 31, v4
	v_and_b32_e32 v10, 3, v2
	v_lshlrev_b64 v[4:5], 7, v[4:5]
	v_lshl_add_u64 v[6:7], s[0:1], 0, v[4:5]
	v_lshlrev_b32_e32 v4, 5, v10
	v_mov_b32_e32 v5, v1
	v_lshl_add_u64 v[6:7], v[6:7], 0, v[4:5]
	global_load_dwordx4 v[96:99], v[6:7], off offset:16 sc1
	global_load_dwordx4 v[100:103], v[6:7], off sc1
	v_mov_b64_e32 v[6:7], s[34:35]
	v_mad_i64_i32 v[6:7], s[34:35], v138, s52, v[6:7]
	s_ashr_i32 s39, s38, 31
	v_lshl_add_u64 v[8:9], s[38:39], 1, v[6:7]
	v_lshl_add_u64 v[8:9], v[8:9], 0, v[4:5]
	global_load_dwordx4 v[112:115], v[8:9], off offset:16 sc1
	global_load_dwordx4 v[116:119], v[8:9], off sc1
	v_lshlrev_b32_e32 v5, 4, v10
	s_cmp_gt_i32 s6, -3
	v_lshlrev_b32_e32 v8, 1, v5
	s_cbranch_scc0 .LBB0_852
	s_add_i32 s5, s2, 0x140
	s_sub_i32 s7, 64, s3
	s_cmp_gt_i32 s6, 1
	s_cselect_b32 s34, s5, s7
	v_add_u32_e32 v12, s34, v138
	v_ashrrev_i32_e32 v13, 31, v12
	v_lshlrev_b64 v[12:13], 7, v[12:13]
	v_lshl_add_u64 v[12:13], s[0:1], 0, v[12:13]
	v_mov_b32_e32 v9, v1
	v_lshl_add_u64 v[12:13], v[12:13], 0, v[8:9]
	s_ashr_i32 s35, s34, 31
	global_load_dwordx4 v[104:107], v[12:13], off offset:16 sc1
	global_load_dwordx4 v[108:111], v[12:13], off sc1
	v_lshl_add_u64 v[12:13], s[34:35], 1, v[6:7]
	v_lshl_add_u64 v[12:13], v[12:13], 0, v[8:9]
	global_load_dwordx4 v[120:123], v[12:13], off offset:16 sc1
	global_load_dwordx4 v[124:127], v[12:13], off sc1
.LBB0_852:
	v_bfe_u32 v9, v138, 1, 3
	v_lshlrev_b32_e32 v10, 1, v10
	v_lshlrev_b32_e32 v5, 4, v9
	v_bitop3_b32 v9, v10, v9, 1 bitop3:0x36
	v_lshlrev_b32_e32 v139, 7, v138
	v_lshlrev_b32_e32 v141, 4, v9
	v_bitop3_b32 v11, v139, v5, v4 bitop3:0xf6
	v_or_b32_e32 v9, v139, v141
	s_waitcnt vmcnt(2)
	ds_write_b128 v11, v[100:103]
	ds_write_b128 v9, v[96:99]
	v_lshl_add_u32 v9, v138, 3, v139
	v_add_u32_e32 v142, v9, v4
	v_add_u32_e32 v143, 0x4000, v142
	v_add_u32_e32 v144, 0x4010, v142
	s_cmp_lt_i32 s6, -1
	s_waitcnt vmcnt(0)
	ds_write2_b64 v143, v[116:117], v[118:119] offset1:1
	ds_write2_b64 v144, v[112:113], v[114:115] offset1:1
	s_waitcnt lgkmcnt(0)
	s_barrier
	s_cbranch_scc1 .LBB0_854
	s_addk_i32 s2, 0x180
	s_sub_i32 s3, 0x80, s3
	s_cmp_gt_i32 s6, 2
	s_cselect_b32 s2, s2, s3
	v_add_u32_e32 v10, s2, v138
	v_ashrrev_i32_e32 v11, 31, v10
	v_lshlrev_b64 v[10:11], 7, v[10:11]
	v_lshl_add_u64 v[10:11], s[0:1], 0, v[10:11]
	v_mov_b32_e32 v9, v1
	v_lshl_add_u64 v[10:11], v[10:11], 0, v[8:9]
	s_ashr_i32 s3, s2, 31
	global_load_dwordx4 v[96:99], v[10:11], off offset:16 sc1
	global_load_dwordx4 v[100:103], v[10:11], off sc1
	v_lshl_add_u64 v[10:11], s[2:3], 1, v[6:7]
	v_lshl_add_u64 v[10:11], v[10:11], 0, v[8:9]
	global_load_dwordx4 v[112:115], v[10:11], off offset:16 sc1
	global_load_dwordx4 v[116:119], v[10:11], off sc1

.LBB0_859:
	v_add_u32_e32 v2, s0, v138
	v_ashrrev_i32_e32 v3, 31, v2
	v_lshlrev_b64 v[2:3], 7, v[2:3]
	v_lshl_add_u64 v[2:3], v[134:135], 0, v[2:3]
	s_ashr_i32 s1, s0, 31
	global_load_dwordx4 v[96:99], v[2:3], off offset:16 sc1
	global_load_dwordx4 v[100:103], v[2:3], off sc1
	v_lshl_add_u64 v[2:3], s[0:1], 1, v[136:137]
	global_load_dwordx4 v[112:115], v[2:3], off offset:16 sc1
	global_load_dwordx4 v[116:119], v[2:3], off sc1

.LBB0_937:
	v_add_u32_e32 v2, s2, v138
	v_ashrrev_i32_e32 v3, 31, v2
	v_lshlrev_b64 v[2:3], 7, v[2:3]
	v_lshl_add_u64 v[2:3], v[134:135], 0, v[2:3]
	s_ashr_i32 s3, s2, 31
	global_load_dwordx4 v[104:107], v[2:3], off offset:16 sc1
	global_load_dwordx4 v[108:111], v[2:3], off sc1
	v_lshl_add_u64 v[2:3], s[2:3], 1, v[136:137]
	global_load_dwordx4 v[120:123], v[2:3], off offset:16 sc1
	global_load_dwordx4 v[124:127], v[2:3], off sc1
	s_andn2_b64 vcc, exec, s[0:1]
	s_cbranch_vccz .LBB0_946

.LBB0_1019:
	s_andn2_b64 vcc, exec, s[0:1]
	s_cbranch_vccnz .LBB0_770
	s_ashr_i32 s2, s9, 7
	s_lshl_b32 s3, s2, 2
	s_or_b32 s3, s3, s37
	s_mul_hi_i32 s5, s3, 0x1100
	s_mul_i32 s4, s3, 0x1100
	s_lshl_b32 s3, s9, 7
	s_and_b32 s3, s3, 0xf80
	s_lshr_b32 s0, s37, 1
	s_lshr_b32 s1, s9, 5
	s_add_i32 s6, s3, 0x100
	s_add_u32 s4, s4, s6
	s_addc_u32 s5, s5, 0
	s_lshl_b64 s[4:5], s[4:5], 7
	s_add_u32 s4, s78, s4
	s_addc_u32 s5, s79, s5
	s_lshl_b32 s10, s2, 1
	s_bfe_u32 s1, s1, 0x10001
	s_or_b32 s1, s1, s10
	s_mul_hi_i32 s33, s1, 0x88000
	s_mul_i32 s1, s1, 0x88000
	s_add_u32 s6, s60, s1
	s_addc_u32 s7, s61, s33
	v_mov_b32_e32 v32, v133
	s_add_u32 s34, s62, s1
	s_movk_i32 s1, 0xffe0
	v_ashrrev_i32_e32 v34, 1, v32
	v_bfi_b32 v2, s1, v34, v32
	v_ashrrev_i32_e32 v3, 31, v2
	v_ashrrev_i32_e32 v20, 2, v32
	s_addc_u32 s35, s63, s33
	v_bfe_u32 v33, v32, 5, 1
	v_lshlrev_b64 v[2:3], 7, v[2:3]
	v_ashrrev_i32_e32 v21, 31, v20
	v_lshl_add_u64 v[2:3], s[4:5], 0, v[2:3]
	v_lshlrev_b32_e32 v0, 4, v33
	v_and_b32_e32 v28, 3, v32
	v_lshlrev_b64 v[22:23], 7, v[20:21]
	v_mov_b64_e32 v[10:11], s[34:35]
	v_lshl_add_u64 v[18:19], v[2:3], 0, v[0:1]
	v_lshl_add_u64 v[2:3], s[6:7], 0, v[22:23]
	v_lshlrev_b32_e32 v0, 5, v28
	v_mad_i64_i32 v[10:11], s[4:5], v20, s52, v[10:11]
	v_lshl_add_u64 v[24:25], v[2:3], 0, v[0:1]
	v_lshl_add_u64 v[26:27], v[10:11], 0, v[0:1]
	global_load_dwordx4 v[2:5], v[24:25], off offset:16 sc1
	global_load_dwordx4 v[6:9], v[24:25], off sc1
	global_load_dwordx4 v[10:13], v[26:27], off sc1
	global_load_dwordx4 v[14:17], v[26:27], off offset:16 sc1
	s_waitcnt vmcnt(13)
	v_lshlrev_b32_e32 v115, 7, v20
	v_bfe_u32 v21, v20, 1, 3
	v_lshlrev_b32_e32 v28, 1, v28
	v_lshlrev_b32_e32 v35, 4, v21
	v_bitop3_b32 v21, v28, v21, 1 bitop3:0x36
	v_lshl_add_u32 v28, v20, 3, v115
	s_waitcnt vmcnt(12)
	v_add_u32_e32 v126, v28, v0
	s_mov_b64 s[4:5], 0x2000
	v_add_co_u32_e32 v28, vcc, s53, v24
	global_load_dwordx4 v[66:69], v[18:19], off sc1
	global_load_dwordx4 v[70:73], v[18:19], off offset:32 sc1
	global_load_dwordx4 v[74:77], v[18:19], off offset:64 sc1
	global_load_dwordx4 v[78:81], v[18:19], off offset:96 sc1
	v_lshl_add_u64 v[18:19], v[24:25], 0, s[4:5]
	v_addc_co_u32_e32 v29, vcc, 0, v25, vcc
	s_mov_b64 s[4:5], 0x4000
	s_movk_i32 s1, 0x4000
	v_lshl_add_u64 v[30:31], v[24:25], 0, s[4:5]
	v_add_co_u32_e32 v24, vcc, s1, v24
	v_lshlrev_b32_e32 v121, 4, v21
	v_bitop3_b32 v36, v115, v35, v0 bitop3:0xf6
	v_addc_co_u32_e32 v25, vcc, 0, v25, vcc
	v_or_b32_e32 v21, v115, v121
	v_add_u32_e32 v127, 0x4000, v126
	v_add_u32_e32 v128, 0x4010, v126
	global_load_dwordx4 v[82:85], v[28:29], off sc1
	global_load_dwordx4 v[86:89], v[18:19], off offset:16 sc1
	global_load_dwordx4 v[94:97], v[26:27], off offset:144 sc1
	global_load_dwordx4 v[102:105], v[26:27], off offset:128 sc1
	s_or_b32 s0, s0, s10
	s_mul_i32 s5, s0, 0x88000
	s_mul_hi_i32 s4, s0, 0x88000
	s_add_u32 s0, s60, s5
	s_addc_u32 s1, s61, s4
	v_and_b32_e32 v134, 31, v32
	v_lshl_add_u64 v[116:117], s[0:1], 0, v[22:23]
	s_add_u32 s0, s62, s5
	s_addc_u32 s1, s63, s4
	v_lshlrev_b32_e32 v114, 3, v33
	v_mov_b32_e32 v142, 0
	v_and_b32_e32 v129, 0xffffffe0, v34
	v_mov_b32_e32 v186, 0xff800000
	s_mov_b32 s4, -2
	v_mov_b32_e32 v18, 0
	v_mov_b32_e32 v19, v142
	v_mov_b32_e32 v22, v142
	v_mov_b32_e32 v23, v142
	v_mov_b32_e32 v28, v142
	v_mov_b32_e32 v29, v142
	s_waitcnt vmcnt(10)
	ds_write_b128 v36, v[6:9]
	ds_write_b128 v21, v[2:5]
	s_waitcnt vmcnt(9)
	ds_write2_b64 v127, v[10:11], v[12:13] offset1:1
	s_waitcnt vmcnt(8)
	ds_write2_b64 v128, v[14:15], v[16:17] offset1:1
	s_waitcnt lgkmcnt(0)
	s_barrier
	global_load_dwordx4 v[90:93], v[24:25], off sc1
	global_load_dwordx4 v[98:101], v[30:31], off offset:16 sc1
	global_load_dwordx4 v[106:109], v[26:27], off offset:272 sc1
	global_load_dwordx4 v[110:113], v[26:27], off offset:256 sc1
	v_lshrrev_b32_e32 v2, 5, v32
	v_bfe_u32 v3, v32, 1, 3
	v_bitop3_b32 v2, v2, v3, 1 bitop3:0x6c
	v_lshlrev_b32_e32 v6, 4, v2
	v_bitop3_b32 v2, v33, v3, 2 bitop3:0x36
	v_lshlrev_b32_e32 v7, 4, v2
	v_bitop3_b32 v2, v33, v3, 4 bitop3:0x36
	v_lshlrev_b32_e32 v8, 4, v2
	v_bitop3_b32 v2, v33, v3, 6 bitop3:0x36
	v_and_b32_e32 v3, 64, v179
	v_lshlrev_b32_e32 v9, 4, v2
	v_xor_b32_e32 v2, 32, v179
	v_add_u32_e32 v3, 64, v3
	v_cmp_lt_i32_e32 vcc, v2, v3
	v_lshlrev_b32_e32 v5, 7, v134
	v_xor_b32_e32 v4, v35, v0
	v_cndmask_b32_e32 v2, v179, v2, vcc
	v_lshlrev_b32_e32 v135, 2, v2
	v_lshl_add_u32 v10, v134, 3, v5
	v_mov_b64_e32 v[2:3], s[0:1]
	v_mad_i64_i32 v[118:119], s[0:1], v20, s52, v[2:3]
	v_add_u32_e32 v136, v5, v6
	v_add_u32_e32 v137, v5, v7
	v_add_u32_e32 v138, v5, v8
	v_add_u32_e32 v139, v5, v9
	v_add_u32_e32 v140, v10, v114
	v_add_u32_e32 v141, v115, v4
	v_mov_b32_e32 v2, 0
	v_mov_b32_e32 v3, v142
	v_mov_b32_e32 v4, v142
	v_mov_b32_e32 v5, v142
	v_mov_b32_e32 v6, v142
	v_mov_b32_e32 v7, v142
	v_mov_b32_e32 v8, v142
	v_mov_b32_e32 v9, v142
	v_mov_b32_e32 v10, v142
	v_mov_b32_e32 v11, v142
	v_mov_b32_e32 v12, v142
	v_mov_b32_e32 v13, v142
	v_mov_b32_e32 v14, v142
	v_mov_b32_e32 v15, v142
	v_mov_b32_e32 v16, v142
	v_mov_b32_e32 v17, v142
	v_mov_b32_e32 v20, v142
	v_mov_b32_e32 v21, v142
	v_mov_b32_e32 v24, v142
	v_mov_b32_e32 v25, v142
	v_mov_b32_e32 v26, v142
	v_mov_b32_e32 v27, v142
	v_mov_b32_e32 v30, v142
	v_mov_b32_e32 v31, v142
	v_mov_b32_e32 v32, v142
	v_mov_b32_e32 v33, v142
	s_branch .LBB0_1022

.LBB0_1022:
	s_add_i32 s4, s4, 2
	v_add_u32_e32 v188, v115, v121
	s_cmp_gt_u32 s4, 64
	ds_read_b128 v[34:37], v136
	ds_read_b128 v[212:215], v137
	ds_read_b128 v[216:219], v138
	ds_read_b128 v[220:223], v139
	ds_read_b128 v[224:227], v136 offset:4096
	ds_read_b128 v[122:125], v137 offset:4096
	ds_read_b128 v[228:231], v138 offset:4096
	ds_read_b128 v[232:235], v139 offset:4096
	s_waitcnt vmcnt(11) lgkmcnt(7)
	s_nop 0
	v_mfma_f32_32x32x16_bf16 v[50:65], v[34:37], v[66:69], 0
	s_waitcnt vmcnt(10) lgkmcnt(6)
	s_nop 0
	v_mfma_f32_32x32x16_bf16 v[50:65], v[212:215], v[70:73], v[50:65]
	s_waitcnt vmcnt(9) lgkmcnt(5)
	s_nop 0
	v_mfma_f32_32x32x16_bf16 v[50:65], v[216:219], v[74:77], v[50:65]
	s_waitcnt vmcnt(8) lgkmcnt(4)
	s_nop 0
	v_mfma_f32_32x32x16_bf16 v[50:65], v[220:223], v[78:81], v[50:65]
	s_waitcnt lgkmcnt(3)
	s_nop 0
	v_mfma_f32_32x32x16_bf16 v[34:49], v[224:227], v[66:69], 0
	s_nop 8
	v_max_f32_e32 v120, v51, v51
	s_waitcnt lgkmcnt(2)
	s_nop 0
	v_mfma_f32_32x32x16_bf16 v[34:49], v[122:125], v[70:73], v[34:49]
	s_waitcnt lgkmcnt(1)
	s_nop 0
	v_mfma_f32_32x32x16_bf16 v[34:49], v[228:231], v[74:77], v[34:49]
	s_waitcnt lgkmcnt(0)
	s_nop 0
	v_mfma_f32_32x32x16_bf16 v[34:49], v[232:235], v[78:81], v[34:49]
	v_max_f32_e32 v122, v50, v50
	v_max_f32_e32 v120, v122, v120
	v_max3_f32 v120, v120, v52, v53
	v_max3_f32 v120, v120, v54, v55
	v_max3_f32 v120, v120, v56, v57
	v_max3_f32 v120, v120, v58, v59
	v_max3_f32 v120, v120, v60, v61
	v_max3_f32 v120, v120, v62, v63
	v_max3_f32 v120, v120, v64, v65
	s_nop 2
	v_max3_f32 v120, v120, v34, v35
	v_max3_f32 v120, v120, v36, v37
	v_max3_f32 v120, v120, v38, v39
	v_max3_f32 v120, v120, v40, v41
	v_max3_f32 v120, v120, v42, v43
	v_max3_f32 v120, v120, v44, v45
	v_max3_f32 v120, v120, v46, v47
	v_max3_f32 v120, v120, v48, v49
	ds_bpermute_b32 v122, v135, v120
	v_lshl_add_u64 v[124:125], v[116:117], 0, v[0:1]
	s_waitcnt lgkmcnt(0)
	v_max3_f32 v187, v186, v120, v122
	v_sub_f32_e32 v34, v34, v187
	v_exp_f32_e32 v159, v34
	v_sub_f32_e32 v34, v35, v187
	v_exp_f32_e32 v160, v34
	v_sub_f32_e32 v34, v36, v187
	v_exp_f32_e32 v161, v34
	v_sub_f32_e32 v34, v37, v187
	v_sub_f32_e32 v50, v50, v187
	v_exp_f32_e32 v162, v34
	v_sub_f32_e32 v34, v38, v187
	v_exp_f32_e32 v143, v50
	v_sub_f32_e32 v50, v51, v187
	v_exp_f32_e32 v163, v34
	v_sub_f32_e32 v34, v39, v187
	v_exp_f32_e32 v144, v50
	v_sub_f32_e32 v50, v52, v187
	v_exp_f32_e32 v164, v34
	v_sub_f32_e32 v34, v40, v187
	v_exp_f32_e32 v145, v50
	v_sub_f32_e32 v50, v53, v187
	v_exp_f32_e32 v165, v34
	v_sub_f32_e32 v34, v41, v187
	v_exp_f32_e32 v146, v50
	v_sub_f32_e32 v50, v54, v187
	v_exp_f32_e32 v166, v34
	v_sub_f32_e32 v34, v42, v187
	v_exp_f32_e32 v147, v50
	v_sub_f32_e32 v50, v55, v187
	v_exp_f32_e32 v167, v34
	v_sub_f32_e32 v34, v43, v187
	v_exp_f32_e32 v148, v50
	v_sub_f32_e32 v50, v56, v187
	v_exp_f32_e32 v168, v34
	v_sub_f32_e32 v34, v44, v187
	v_sub_f32_e32 v120, v186, v187
	v_exp_f32_e32 v149, v50
	v_sub_f32_e32 v50, v57, v187
	v_exp_f32_e32 v169, v34
	v_sub_f32_e32 v34, v45, v187
	v_exp_f32_e32 v150, v50
	v_exp_f32_e32 v181, v34
	v_sub_f32_e32 v34, v46, v187
	v_exp_f32_e32 v120, v120
	v_add_u32_e32 v46, 0x4000, v140
	v_exp_f32_e32 v182, v34
	v_sub_f32_e32 v34, v47, v187
	ds_read2_b64 v[38:41], v46 offset1:2
	ds_read2_b64 v[42:45], v46 offset0:4 offset1:6
	v_exp_f32_e32 v183, v34
	v_sub_f32_e32 v34, v48, v187
	v_exp_f32_e32 v184, v34
	v_sub_f32_e32 v34, v49, v187
	v_exp_f32_e32 v185, v34
	v_pk_mul_f32 v[32:33], v[32:33], v[120:121] op_sel_hi:[1,0]
	v_pk_mul_f32 v[30:31], v[30:31], v[120:121] op_sel_hi:[1,0]
	v_pk_mul_f32 v[28:29], v[28:29], v[120:121] op_sel_hi:[1,0]
	v_pk_mul_f32 v[26:27], v[26:27], v[120:121] op_sel_hi:[1,0]
	v_pk_mul_f32 v[24:25], v[24:25], v[120:121] op_sel_hi:[1,0]
	v_pk_mul_f32 v[22:23], v[22:23], v[120:121] op_sel_hi:[1,0]
	v_pk_mul_f32 v[20:21], v[20:21], v[120:121] op_sel_hi:[1,0]
	v_pk_mul_f32 v[18:19], v[18:19], v[120:121] op_sel_hi:[1,0]
	v_cvt_pk_bf16_f32 v34, v143, v144
	v_cvt_pk_bf16_f32 v35, v145, v146
	v_cvt_pk_bf16_f32 v36, v147, v148
	v_cvt_pk_bf16_f32 v37, v149, v150
	v_add_u32_e32 v47, 0x5000, v140
	v_sub_f32_e32 v50, v58, v187
	s_waitcnt lgkmcnt(1)
	v_mfma_f32_32x32x16_bf16 v[18:33], v[38:41], v[34:37], v[18:33]
	ds_read2_b64 v[38:41], v47 offset0:32 offset1:34
	v_exp_f32_e32 v151, v50
	v_sub_f32_e32 v50, v59, v187
	v_exp_f32_e32 v152, v50
	v_sub_f32_e32 v50, v60, v187
	v_exp_f32_e32 v153, v50
	v_sub_f32_e32 v50, v61, v187
	v_pk_mul_f32 v[16:17], v[16:17], v[120:121] op_sel_hi:[1,0]
	v_pk_mul_f32 v[14:15], v[14:15], v[120:121] op_sel_hi:[1,0]
	v_pk_mul_f32 v[12:13], v[12:13], v[120:121] op_sel_hi:[1,0]
	v_pk_mul_f32 v[10:11], v[10:11], v[120:121] op_sel_hi:[1,0]
	v_pk_mul_f32 v[8:9], v[8:9], v[120:121] op_sel_hi:[1,0]
	v_pk_mul_f32 v[6:7], v[6:7], v[120:121] op_sel_hi:[1,0]
	v_pk_mul_f32 v[4:5], v[4:5], v[120:121] op_sel_hi:[1,0]
	v_pk_mul_f32 v[2:3], v[2:3], v[120:121] op_sel_hi:[1,0]
	v_exp_f32_e32 v154, v50
	v_sub_f32_e32 v50, v62, v187
	s_waitcnt lgkmcnt(0)
	v_mfma_f32_32x32x16_bf16 v[2:17], v[38:41], v[34:37], v[2:17]
	ds_read2_b64 v[38:41], v47 offset0:36 offset1:38
	v_exp_f32_e32 v155, v50
	v_sub_f32_e32 v50, v63, v187
	v_exp_f32_e32 v156, v50
	v_sub_f32_e32 v50, v64, v187
	v_exp_f32_e32 v157, v50
	v_sub_f32_e32 v50, v65, v187
	v_exp_f32_e32 v158, v50
	v_cvt_pk_bf16_f32 v34, v151, v152
	v_cvt_pk_bf16_f32 v35, v153, v154
	v_cvt_pk_bf16_f32 v36, v155, v156
	v_cvt_pk_bf16_f32 v37, v157, v158
	v_lshl_add_u64 v[122:123], v[118:119], 0, v[0:1]
	s_waitcnt lgkmcnt(0)
	v_mfma_f32_32x32x16_bf16 v[2:17], v[38:41], v[34:37], v[2:17]
	ds_read2_b64 v[38:41], v46 offset0:8 offset1:10
	v_mfma_f32_32x32x16_bf16 v[18:33], v[42:45], v[34:37], v[18:33]
	v_cvt_pk_bf16_f32 v34, v159, v160
	v_cvt_pk_bf16_f32 v35, v161, v162
	v_cvt_pk_bf16_f32 v36, v163, v164
	v_cvt_pk_bf16_f32 v37, v165, v166
	s_waitcnt lgkmcnt(0)
	s_nop 0
	v_mfma_f32_32x32x16_bf16 v[18:33], v[38:41], v[34:37], v[18:33]
	ds_read2_b64 v[38:41], v47 offset0:40 offset1:42
	s_waitcnt lgkmcnt(0)
	v_mfma_f32_32x32x16_bf16 v[2:17], v[38:41], v[34:37], v[2:17]
	ds_read2_b64 v[38:41], v46 offset0:12 offset1:14
	v_cvt_pk_bf16_f32 v34, v167, v168
	v_cvt_pk_bf16_f32 v35, v169, v181
	v_cvt_pk_bf16_f32 v36, v182, v183
	v_cvt_pk_bf16_f32 v37, v184, v185
	s_waitcnt lgkmcnt(0)
	s_nop 0
	v_mfma_f32_32x32x16_bf16 v[18:33], v[38:41], v[34:37], v[18:33]
	ds_read2_b64 v[38:41], v47 offset0:44 offset1:46
	s_waitcnt vmcnt(3)
	ds_write_b128 v141, v[82:85] offset:8192
	s_waitcnt vmcnt(2)
	ds_write_b128 v188, v[86:89] offset:8192
	s_waitcnt lgkmcnt(2)
	v_mfma_f32_32x32x16_bf16 v[2:17], v[38:41], v[34:37], v[2:17]
	v_add_u32_e32 v34, 0x6200, v126
	s_waitcnt vmcnt(0)
	ds_write2_b64 v34, v[102:103], v[104:105] offset1:1
	v_add_u32_e32 v34, 0x6210, v126
	ds_write2_b64 v34, v[94:95], v[96:97] offset1:1
	s_waitcnt lgkmcnt(0)
	s_barrier
	s_cbranch_scc1 .LBB0_1024
	v_add_co_u32_e32 v36, vcc, 0x6000, v124
	s_mov_b64 s[0:1], 0x6000
	s_nop 0
	v_addc_co_u32_e32 v37, vcc, 0, v125, vcc
	v_lshl_add_u64 v[34:35], v[124:125], 0, s[0:1]
	global_load_dwordx4 v[82:85], v[36:37], off sc1
	global_load_dwordx4 v[86:89], v[34:35], off offset:16 sc1
	global_load_dwordx4 v[94:97], v[122:123], off offset:400 sc1
	global_load_dwordx4 v[102:105], v[122:123], off offset:384 sc1

.LBB0_1026:
	s_cmp_gt_u32 s4, 63
	s_waitcnt lgkmcnt(0)
	s_barrier
	s_cbranch_scc1 .LBB0_1021
	s_waitcnt vmcnt(3)
	v_add_co_u32_e32 v90, vcc, 0x8000, v124
	s_waitcnt vmcnt(2)
	v_lshl_add_u64 v[98:99], v[124:125], 0, s[28:29]
	v_addc_co_u32_e32 v91, vcc, 0, v125, vcc
	global_load_dwordx4 v[90:93], v[90:91], off sc1
	s_nop 0
	global_load_dwordx4 v[98:101], v[98:99], off offset:16 sc1
	s_nop 0
	global_load_dwordx4 v[106:109], v[122:123], off offset:528 sc1
	global_load_dwordx4 v[110:113], v[122:123], off offset:512 sc1
	s_branch .LBB0_1021

.LBB0_1063:
	s_andn2_b64 vcc, exec, s[0:1]
	s_cbranch_vccnz .LBB0_1071
	v_readlane_b32 s0, v207, 5
	v_readlane_b32 s1, v207, 6
	s_and_b64 s[0:1], s[0:1], exec
	v_readlane_b32 s0, v208, 26
	s_cselect_b32 s0, s0, s97
	s_and_b32 s7, s0, 3
	s_lshr_b32 s6, s0, 2
	s_lshr_b32 s9, s0, 5
	s_lshl_b32 s2, s6, 5
	s_and_b32 s2, s2, 0xc0
	s_and_b32 s3, s6, 1
	v_readlane_b32 s4, v210, 50
	v_readlane_b32 s5, v210, 51
	v_readlane_b32 s52, v210, 32
	v_readlane_b32 s53, v210, 33
	v_readlane_b32 s8, v208, 60
	s_cmp_eq_u32 s3, 0
	s_cselect_b32 s46, s14, s16
	s_cselect_b32 s47, s15, s17
	s_cselect_b32 s48, s18, s20
	s_cselect_b32 s49, s19, s21
	s_cselect_b32 s50, s26, s4
	s_cselect_b32 s51, s27, s5
	s_cselect_b32 s34, 16, -16
	s_cselect_b32 s10, 1, -1
	s_cselect_b32 s54, 0, 0xff
	s_cselect_b32 s55, 0, 0xfff
	s_lshl_b32 s0, s9, 8
	s_add_i32 s0, s0, 0x4000
	s_add_i32 s54, s54, s0
	s_lshl_b32 s0, s9, 12
	s_add_i32 s55, s55, s0
	s_setprio 3
	v_lshrrev_b32_e32 v119, 4, v133
	v_and_b32_e32 v120, 15, v133
	v_and_b32_e32 v121, 12, v120
	v_and_b32_e32 v0, 1, v120
	v_lshl_or_b32 v121, v0, 1, v121
	v_bfe_u32 v0, v120, 1, 1
	v_or_b32_e32 v121, v121, v0
	v_mul_i32_i24_e32 v0, s10, v119
	v_add_u32_e32 v113, s54, v0
	v_add_u32_e32 v117, s55, v0
	v_mul_i32_i24_e32 v0, s10, v121
	v_add_u32_e32 v114, s54, v0
	v_add_u32_e32 v126, s55, v0
	v_and_b32_e32 v0, 8, v120
	v_cmp_ne_u32_e64 s[38:39], 0, v0
	v_and_b32_e32 v0, 4, v120
	v_cmp_ne_u32_e64 s[40:41], 0, v0
	v_and_b32_e32 v0, 1, v120
	v_cmp_ne_u32_e64 s[42:43], 0, v0
	v_and_b32_e32 v0, 2, v120
	v_cmp_ne_u32_e64 s[44:45], 0, v0
	v_lshlrev_b32_e32 v0, 4, v120
	s_lshl_b32 s0, s2, 2
	v_add_u32_e32 v115, s0, v0
	s_lshl_b32 s1, s7, 4
	v_add_u32_e32 v122, s1, v119
	v_lshl_add_u32 v116, v122, 2, s0
	v_mov_b32_e32 v110, v0
	v_lshlrev_b32_e32 v111, 2, v122
	v_lshl_add_u32 v112, v119, 8, v0
	s_lshl_b32 s8, s8, 10
	s_add_u32 s52, s52, s8
	s_addc_u32 s53, s53, 0
	global_load_dwordx4 v[6:9], v115, s[52:53]
	v_mov_b32_e32 v2, 0
	v_mov_b32_e32 v3, 0
	v_mov_b32_e32 v4, 0
	v_mov_b32_e32 v5, 0
	v_mov_b32_e32 v82, 0
	v_mov_b32_e32 v83, 0
	v_mov_b32_e32 v84, 0
	v_mov_b32_e32 v85, 0
	v_mov_b32_e32 v92, 0
	s_mov_b32 s33, 0
	v_mul_u32_u24_e32 v0, 0xf00, v113
	v_lshl_add_u32 v125, v113, 10, v115
	v_add_u32_e32 v0, v0, v115
	v_add_u32_e32 v113, s34, v113
	global_load_dwordx4 v[22:25], v125, s[46:47] sc1
	global_load_dwordx4 v[26:29], v125, s[48:49] sc1
	global_load_dwordx4 v[30:33], v125, s[22:23] sc1
	global_load_dwordx4 v[14:17], v0, s[12:13] offset:1024 sc1
	global_load_dwordx4 v[10:13], v0, s[12:13] sc1
	global_load_dwordx4 v[18:21], v0, s[12:13] offset:2048 sc1
	s_waitcnt vmcnt(0)
	v_pk_add_f32 v[122:123], v[26:27], -1.0 op_sel_hi:[1,0]
	v_pk_add_f32 v[124:125], v[28:29], -1.0 op_sel_hi:[1,0]
	v_pk_mul_f32 v[118:119], v[30:31], v[26:27]
	v_pk_fma_f32 v[122:123], v[6:7], v[122:123], 1.0 op_sel_hi:[1,1,0]
	v_pk_fma_f32 v[124:125], v[8:9], v[124:125], 1.0 op_sel_hi:[1,1,0]
	v_pk_mul_f32 v[120:121], v[32:33], v[28:29]
	v_pk_mul_f32 v[122:123], v[14:15], v[122:123]
	v_pk_mul_f32 v[124:125], v[16:17], v[124:125]
	ds_write_b128 v112, v[22:25] offset:0
	ds_write_b128 v112, v[30:33] offset:4096
	ds_write_b128 v112, v[10:13] offset:16384
	ds_write_b128 v112, v[18:21] offset:20480
	ds_write_b128 v112, v[118:121] offset:8192
	ds_write_b128 v112, v[122:125] offset:12288
	s_waitcnt lgkmcnt(0)
	v_xor_b32_e32 v112, 0x6000, v112
	v_mul_u32_u24_e32 v0, 0xf00, v113
	v_lshl_add_u32 v125, v113, 10, v115
	v_add_u32_e32 v0, v0, v115
	v_add_u32_e32 v113, s34, v113
	global_load_dwordx4 v[146:149], v125, s[46:47] sc1
	global_load_dwordx4 v[150:153], v125, s[48:49] sc1
	global_load_dwordx4 v[154:157], v125, s[22:23] sc1
	global_load_dwordx4 v[138:141], v0, s[12:13] offset:1024 sc1
	global_load_dwordx4 v[134:137], v0, s[12:13] sc1
	global_load_dwordx4 v[142:145], v0, s[12:13] offset:2048 sc1
	s_barrier
.Lscan_chunk:
	ds_read_b128 v[38:41], v110 offset:4096
	ds_read_b128 v[34:37], v110 offset:0
	ds_read_b128 v[46:49], v110 offset:12288
	ds_read_b32 v54, v111 offset:20480
	ds_read_b128 v[42:45], v110 offset:8192
	ds_read_b128 v[50:53], v110 offset:16384
	ds_read_b128 v[60:63], v110 offset:4352
	ds_read_b128 v[56:59], v110 offset:256
	ds_read_b128 v[68:71], v110 offset:12544
	ds_read_b32 v76, v111 offset:20736
	ds_read_b128 v[64:67], v110 offset:8448
	ds_read_b128 v[72:75], v110 offset:16640
	s_cmpk_ge_i32 s33, 0x10e
	s_cbranch_scc1 .Lscan_skipload_a
	v_mul_u32_u24_e32 v0, 0xf00, v113
	v_lshl_add_u32 v125, v113, 10, v115
	v_add_u32_e32 v0, v0, v115
	v_add_u32_e32 v113, s34, v113
	global_load_dwordx4 v[22:25], v125, s[46:47] sc1
	global_load_dwordx4 v[26:29], v125, s[48:49] sc1
	global_load_dwordx4 v[30:33], v125, s[22:23] sc1
	global_load_dwordx4 v[14:17], v0, s[12:13] offset:1024 sc1
	global_load_dwordx4 v[10:13], v0, s[12:13] sc1
	global_load_dwordx4 v[18:21], v0, s[12:13] offset:2048 sc1
	s_cmp_eq_u32 s33, 13
	s_cbranch_scc0 .Lscan_nogload_a
	v_mov_b32_e32 v113, v117
	s_branch .Lscan_nogload_a

.Lscan_nored_a:
	s_waitcnt lgkmcnt(1)
	v_pk_mul_f32 v[86:87], v[2:3], v[38:39]
	v_pk_mul_f32 v[78:79], v[2:3], v[34:35]
	v_pk_fma_f32 v[86:87], v[4:5], v[40:41], v[86:87]
	v_pk_mul_f32 v[80:81], v[4:5], v[36:37]
	ds_read_b128 v[38:41], v110 offset:4608
	v_add_f32_e32 v90, v86, v87
	v_pk_fma_f32 v[82:83], v[54:55], v[46:47], v[78:79] op_sel_hi:[0,1,1]
	ds_read_b128 v[34:37], v110 offset:512
	v_add_f32_dpp v90, v90, v90 quad_perm:[1,0,3,2] row_mask:0xf bank_mask:0xf bound_ctrl:1
	v_pk_fma_f32 v[84:85], v[54:55], v[48:49], v[80:81] op_sel_hi:[0,1,1]
	ds_read_b128 v[46:49], v110 offset:12800
	v_add_f32_dpp v90, v90, v90 quad_perm:[2,3,0,1] row_mask:0xf bank_mask:0xf bound_ctrl:1
	ds_read_b32 v54, v111 offset:20992
	s_nop 0
	v_add_f32_dpp v90, v90, v90 row_half_mirror row_mask:0xf bank_mask:0xf bound_ctrl:1
	s_nop 0
	s_nop 0
	v_add_f32_dpp v92, v90, v90 row_mirror row_mask:0xf bank_mask:0xf bound_ctrl:1
	v_pk_fma_f32 v[2:3], v[92:93], v[42:43], v[82:83] op_sel_hi:[0,1,1] neg_lo:[1,0,0] neg_hi:[1,0,0]
	v_pk_fma_f32 v[4:5], v[92:93], v[44:45], v[84:85] op_sel_hi:[0,1,1] neg_lo:[1,0,0] neg_hi:[1,0,0]
	ds_read_b128 v[42:45], v110 offset:8704
	v_pk_mul_f32 v[86:87], v[2:3], v[60:61]
	v_pk_mul_f32 v[78:79], v[2:3], v[56:57]
	v_pk_fma_f32 v[86:87], v[4:5], v[62:63], v[86:87]
	v_pk_mul_f32 v[80:81], v[4:5], v[58:59]
	v_pk_mul_f32 v[88:89], v[2:3], v[50:51]
	v_add_f32_e32 v90, v86, v87
	v_pk_fma_f32 v[82:83], v[76:77], v[68:69], v[78:79] op_sel_hi:[0,1,1]
	v_pk_fma_f32 v[88:89], v[4:5], v[52:53], v[88:89]
	v_add_f32_dpp v90, v90, v90 quad_perm:[1,0,3,2] row_mask:0xf bank_mask:0xf bound_ctrl:1
	v_pk_fma_f32 v[84:85], v[76:77], v[70:71], v[80:81] op_sel_hi:[0,1,1]
	ds_read_b128 v[60:63], v110 offset:4864
	v_add_f32_dpp v90, v90, v90 quad_perm:[2,3,0,1] row_mask:0xf bank_mask:0xf bound_ctrl:1
	ds_read_b128 v[56:59], v110 offset:768
	v_add_f32_e32 v94, v88, v89
	v_add_f32_dpp v90, v90, v90 row_half_mirror row_mask:0xf bank_mask:0xf bound_ctrl:1
	ds_read_b128 v[50:53], v110 offset:16896
	ds_read_b128 v[68:71], v110 offset:13056
	v_add_f32_dpp v92, v90, v90 row_mirror row_mask:0xf bank_mask:0xf bound_ctrl:1
	ds_read_b32 v76, v111 offset:21248
	v_pk_fma_f32 v[2:3], v[92:93], v[64:65], v[82:83] op_sel_hi:[0,1,1] neg_lo:[1,0,0] neg_hi:[1,0,0]
	v_pk_fma_f32 v[4:5], v[92:93], v[66:67], v[84:85] op_sel_hi:[0,1,1] neg_lo:[1,0,0] neg_hi:[1,0,0]
	ds_read_b128 v[64:67], v110 offset:8960
	s_waitcnt lgkmcnt(6)
	v_pk_mul_f32 v[86:87], v[2:3], v[38:39]
	v_pk_mul_f32 v[78:79], v[2:3], v[34:35]
	v_pk_fma_f32 v[86:87], v[4:5], v[40:41], v[86:87]
	v_pk_mul_f32 v[80:81], v[4:5], v[36:37]
	v_pk_mul_f32 v[88:89], v[2:3], v[72:73]
	v_add_f32_e32 v90, v86, v87
	v_pk_fma_f32 v[82:83], v[54:55], v[46:47], v[78:79] op_sel_hi:[0,1,1]
	v_pk_fma_f32 v[88:89], v[4:5], v[74:75], v[88:89]
	v_add_f32_dpp v90, v90, v90 quad_perm:[1,0,3,2] row_mask:0xf bank_mask:0xf bound_ctrl:1
	v_pk_fma_f32 v[84:85], v[54:55], v[48:49], v[80:81] op_sel_hi:[0,1,1]
	ds_read_b128 v[38:41], v110 offset:5120
	v_add_f32_dpp v90, v90, v90 quad_perm:[2,3,0,1] row_mask:0xf bank_mask:0xf bound_ctrl:1
	ds_read_b128 v[34:37], v110 offset:1024
	v_add_f32_e32 v95, v88, v89
	v_add_f32_dpp v90, v90, v90 row_half_mirror row_mask:0xf bank_mask:0xf bound_ctrl:1
	ds_read_b128 v[72:75], v110 offset:17152
	ds_read_b128 v[46:49], v110 offset:13312
	v_add_f32_dpp v92, v90, v90 row_mirror row_mask:0xf bank_mask:0xf bound_ctrl:1
	ds_read_b32 v54, v111 offset:21504
	v_pk_fma_f32 v[2:3], v[92:93], v[42:43], v[82:83] op_sel_hi:[0,1,1] neg_lo:[1,0,0] neg_hi:[1,0,0]
	v_pk_fma_f32 v[4:5], v[92:93], v[44:45], v[84:85] op_sel_hi:[0,1,1] neg_lo:[1,0,0] neg_hi:[1,0,0]
	ds_read_b128 v[42:45], v110 offset:9216
	s_waitcnt lgkmcnt(6)
	v_pk_mul_f32 v[86:87], v[2:3], v[60:61]
	v_pk_mul_f32 v[78:79], v[2:3], v[56:57]
	v_pk_fma_f32 v[86:87], v[4:5], v[62:63], v[86:87]
	v_pk_mul_f32 v[80:81], v[4:5], v[58:59]
	v_pk_mul_f32 v[88:89], v[2:3], v[50:51]
	v_add_f32_e32 v90, v86, v87
	v_pk_fma_f32 v[82:83], v[76:77], v[68:69], v[78:79] op_sel_hi:[0,1,1]
	v_pk_fma_f32 v[88:89], v[4:5], v[52:53], v[88:89]
	v_add_f32_dpp v90, v90, v90 quad_perm:[1,0,3,2] row_mask:0xf bank_mask:0xf bound_ctrl:1
	v_pk_fma_f32 v[84:85], v[76:77], v[70:71], v[80:81] op_sel_hi:[0,1,1]
	ds_read_b128 v[60:63], v110 offset:5376
	v_add_f32_dpp v90, v90, v90 quad_perm:[2,3,0,1] row_mask:0xf bank_mask:0xf bound_ctrl:1
	ds_read_b128 v[56:59], v110 offset:1280
	v_add_f32_e32 v96, v88, v89
	v_add_f32_dpp v90, v90, v90 row_half_mirror row_mask:0xf bank_mask:0xf bound_ctrl:1
	ds_read_b128 v[50:53], v110 offset:17408
	ds_read_b128 v[68:71], v110 offset:13568
	v_add_f32_dpp v92, v90, v90 row_mirror row_mask:0xf bank_mask:0xf bound_ctrl:1
	ds_read_b32 v76, v111 offset:21760
	v_pk_fma_f32 v[2:3], v[92:93], v[64:65], v[82:83] op_sel_hi:[0,1,1] neg_lo:[1,0,0] neg_hi:[1,0,0]
	v_pk_fma_f32 v[4:5], v[92:93], v[66:67], v[84:85] op_sel_hi:[0,1,1] neg_lo:[1,0,0] neg_hi:[1,0,0]
	ds_read_b128 v[64:67], v110 offset:9472
	s_waitcnt lgkmcnt(6)
	v_pk_mul_f32 v[86:87], v[2:3], v[38:39]
	v_pk_mul_f32 v[78:79], v[2:3], v[34:35]
	v_pk_fma_f32 v[86:87], v[4:5], v[40:41], v[86:87]
	v_pk_mul_f32 v[80:81], v[4:5], v[36:37]
	v_pk_mul_f32 v[88:89], v[2:3], v[72:73]
	v_add_f32_e32 v90, v86, v87
	v_pk_fma_f32 v[82:83], v[54:55], v[46:47], v[78:79] op_sel_hi:[0,1,1]
	v_pk_fma_f32 v[88:89], v[4:5], v[74:75], v[88:89]
	v_add_f32_dpp v90, v90, v90 quad_perm:[1,0,3,2] row_mask:0xf bank_mask:0xf bound_ctrl:1
	v_pk_fma_f32 v[84:85], v[54:55], v[48:49], v[80:81] op_sel_hi:[0,1,1]
	ds_read_b128 v[38:41], v110 offset:5632
	v_add_f32_dpp v90, v90, v90 quad_perm:[2,3,0,1] row_mask:0xf bank_mask:0xf bound_ctrl:1
	ds_read_b128 v[34:37], v110 offset:1536
	v_add_f32_e32 v97, v88, v89
	v_add_f32_dpp v90, v90, v90 row_half_mirror row_mask:0xf bank_mask:0xf bound_ctrl:1
	ds_read_b128 v[72:75], v110 offset:17664
	ds_read_b128 v[46:49], v110 offset:13824
	v_add_f32_dpp v92, v90, v90 row_mirror row_mask:0xf bank_mask:0xf bound_ctrl:1
	ds_read_b32 v54, v111 offset:22016
	v_pk_fma_f32 v[2:3], v[92:93], v[42:43], v[82:83] op_sel_hi:[0,1,1] neg_lo:[1,0,0] neg_hi:[1,0,0]
	v_pk_fma_f32 v[4:5], v[92:93], v[44:45], v[84:85] op_sel_hi:[0,1,1] neg_lo:[1,0,0] neg_hi:[1,0,0]
	ds_read_b128 v[42:45], v110 offset:9728
	s_waitcnt lgkmcnt(6)
	v_pk_mul_f32 v[86:87], v[2:3], v[60:61]
	v_pk_mul_f32 v[78:79], v[2:3], v[56:57]
	v_pk_fma_f32 v[86:87], v[4:5], v[62:63], v[86:87]
	v_pk_mul_f32 v[80:81], v[4:5], v[58:59]
	v_pk_mul_f32 v[88:89], v[2:3], v[50:51]
	v_add_f32_e32 v90, v86, v87
	v_pk_fma_f32 v[82:83], v[76:77], v[68:69], v[78:79] op_sel_hi:[0,1,1]
	v_pk_fma_f32 v[88:89], v[4:5], v[52:53], v[88:89]
	v_add_f32_dpp v90, v90, v90 quad_perm:[1,0,3,2] row_mask:0xf bank_mask:0xf bound_ctrl:1
	v_pk_fma_f32 v[84:85], v[76:77], v[70:71], v[80:81] op_sel_hi:[0,1,1]
	ds_read_b128 v[60:63], v110 offset:5888
	v_add_f32_dpp v90, v90, v90 quad_perm:[2,3,0,1] row_mask:0xf bank_mask:0xf bound_ctrl:1
	ds_read_b128 v[56:59], v110 offset:1792
	v_add_f32_e32 v98, v88, v89
	v_add_f32_dpp v90, v90, v90 row_half_mirror row_mask:0xf bank_mask:0xf bound_ctrl:1
	ds_read_b128 v[50:53], v110 offset:17920
	ds_read_b128 v[68:71], v110 offset:14080
	v_add_f32_dpp v92, v90, v90 row_mirror row_mask:0xf bank_mask:0xf bound_ctrl:1
	ds_read_b32 v76, v111 offset:22272
	v_pk_fma_f32 v[2:3], v[92:93], v[64:65], v[82:83] op_sel_hi:[0,1,1] neg_lo:[1,0,0] neg_hi:[1,0,0]
	v_pk_fma_f32 v[4:5], v[92:93], v[66:67], v[84:85] op_sel_hi:[0,1,1] neg_lo:[1,0,0] neg_hi:[1,0,0]
	ds_read_b128 v[64:67], v110 offset:9984
	s_waitcnt lgkmcnt(6)
	v_pk_mul_f32 v[86:87], v[2:3], v[38:39]
	v_pk_mul_f32 v[78:79], v[2:3], v[34:35]
	v_pk_fma_f32 v[86:87], v[4:5], v[40:41], v[86:87]
	v_pk_mul_f32 v[80:81], v[4:5], v[36:37]
	v_pk_mul_f32 v[88:89], v[2:3], v[72:73]
	v_add_f32_e32 v90, v86, v87
	v_pk_fma_f32 v[82:83], v[54:55], v[46:47], v[78:79] op_sel_hi:[0,1,1]
	v_pk_fma_f32 v[88:89], v[4:5], v[74:75], v[88:89]
	v_add_f32_dpp v90, v90, v90 quad_perm:[1,0,3,2] row_mask:0xf bank_mask:0xf bound_ctrl:1
	v_pk_fma_f32 v[84:85], v[54:55], v[48:49], v[80:81] op_sel_hi:[0,1,1]
	ds_read_b128 v[38:41], v110 offset:6144
	v_add_f32_dpp v90, v90, v90 quad_perm:[2,3,0,1] row_mask:0xf bank_mask:0xf bound_ctrl:1
	ds_read_b128 v[34:37], v110 offset:2048
	v_add_f32_e32 v99, v88, v89
	v_add_f32_dpp v90, v90, v90 row_half_mirror row_mask:0xf bank_mask:0xf bound_ctrl:1
	ds_read_b128 v[72:75], v110 offset:18176
	ds_read_b128 v[46:49], v110 offset:14336
	v_add_f32_dpp v92, v90, v90 row_mirror row_mask:0xf bank_mask:0xf bound_ctrl:1
	ds_read_b32 v54, v111 offset:22528
	v_pk_fma_f32 v[2:3], v[92:93], v[42:43], v[82:83] op_sel_hi:[0,1,1] neg_lo:[1,0,0] neg_hi:[1,0,0]
	v_pk_fma_f32 v[4:5], v[92:93], v[44:45], v[84:85] op_sel_hi:[0,1,1] neg_lo:[1,0,0] neg_hi:[1,0,0]
	ds_read_b128 v[42:45], v110 offset:10240
	s_waitcnt lgkmcnt(6)
	v_pk_mul_f32 v[86:87], v[2:3], v[60:61]
	v_pk_mul_f32 v[78:79], v[2:3], v[56:57]
	v_pk_fma_f32 v[86:87], v[4:5], v[62:63], v[86:87]
	v_pk_mul_f32 v[80:81], v[4:5], v[58:59]
	v_pk_mul_f32 v[88:89], v[2:3], v[50:51]
	v_add_f32_e32 v90, v86, v87
	v_pk_fma_f32 v[82:83], v[76:77], v[68:69], v[78:79] op_sel_hi:[0,1,1]
	v_pk_fma_f32 v[88:89], v[4:5], v[52:53], v[88:89]
	v_add_f32_dpp v90, v90, v90 quad_perm:[1,0,3,2] row_mask:0xf bank_mask:0xf bound_ctrl:1
	v_pk_fma_f32 v[84:85], v[76:77], v[70:71], v[80:81] op_sel_hi:[0,1,1]
	ds_read_b128 v[60:63], v110 offset:6400
	v_add_f32_dpp v90, v90, v90 quad_perm:[2,3,0,1] row_mask:0xf bank_mask:0xf bound_ctrl:1
	ds_read_b128 v[56:59], v110 offset:2304
	v_add_f32_e32 v100, v88, v89
	v_add_f32_dpp v90, v90, v90 row_half_mirror row_mask:0xf bank_mask:0xf bound_ctrl:1
	ds_read_b128 v[50:53], v110 offset:18432
	ds_read_b128 v[68:71], v110 offset:14592
	v_add_f32_dpp v92, v90, v90 row_mirror row_mask:0xf bank_mask:0xf bound_ctrl:1
	ds_read_b32 v76, v111 offset:22784
	v_pk_fma_f32 v[2:3], v[92:93], v[64:65], v[82:83] op_sel_hi:[0,1,1] neg_lo:[1,0,0] neg_hi:[1,0,0]
	v_pk_fma_f32 v[4:5], v[92:93], v[66:67], v[84:85] op_sel_hi:[0,1,1] neg_lo:[1,0,0] neg_hi:[1,0,0]
	ds_read_b128 v[64:67], v110 offset:10496
	s_waitcnt lgkmcnt(6)
	v_pk_mul_f32 v[86:87], v[2:3], v[38:39]
	v_pk_mul_f32 v[78:79], v[2:3], v[34:35]
	v_pk_fma_f32 v[86:87], v[4:5], v[40:41], v[86:87]
	v_pk_mul_f32 v[80:81], v[4:5], v[36:37]
	v_pk_mul_f32 v[88:89], v[2:3], v[72:73]
	v_add_f32_e32 v90, v86, v87
	v_pk_fma_f32 v[82:83], v[54:55], v[46:47], v[78:79] op_sel_hi:[0,1,1]
	v_pk_fma_f32 v[88:89], v[4:5], v[74:75], v[88:89]
	v_add_f32_dpp v90, v90, v90 quad_perm:[1,0,3,2] row_mask:0xf bank_mask:0xf bound_ctrl:1
	v_pk_fma_f32 v[84:85], v[54:55], v[48:49], v[80:81] op_sel_hi:[0,1,1]
	ds_read_b128 v[38:41], v110 offset:6656
	v_add_f32_dpp v90, v90, v90 quad_perm:[2,3,0,1] row_mask:0xf bank_mask:0xf bound_ctrl:1
	ds_read_b128 v[34:37], v110 offset:2560
	v_add_f32_e32 v101, v88, v89
	v_add_f32_dpp v90, v90, v90 row_half_mirror row_mask:0xf bank_mask:0xf bound_ctrl:1
	ds_read_b128 v[72:75], v110 offset:18688
	ds_read_b128 v[46:49], v110 offset:14848
	v_add_f32_dpp v92, v90, v90 row_mirror row_mask:0xf bank_mask:0xf bound_ctrl:1
	ds_read_b32 v54, v111 offset:23040
	v_pk_fma_f32 v[2:3], v[92:93], v[42:43], v[82:83] op_sel_hi:[0,1,1] neg_lo:[1,0,0] neg_hi:[1,0,0]
	v_pk_fma_f32 v[4:5], v[92:93], v[44:45], v[84:85] op_sel_hi:[0,1,1] neg_lo:[1,0,0] neg_hi:[1,0,0]
	ds_read_b128 v[42:45], v110 offset:10752
	s_waitcnt lgkmcnt(6)
	v_pk_mul_f32 v[86:87], v[2:3], v[60:61]
	v_pk_mul_f32 v[78:79], v[2:3], v[56:57]
	v_pk_fma_f32 v[86:87], v[4:5], v[62:63], v[86:87]
	v_pk_mul_f32 v[80:81], v[4:5], v[58:59]
	v_pk_mul_f32 v[88:89], v[2:3], v[50:51]
	v_add_f32_e32 v90, v86, v87
	v_pk_fma_f32 v[82:83], v[76:77], v[68:69], v[78:79] op_sel_hi:[0,1,1]
	v_pk_fma_f32 v[88:89], v[4:5], v[52:53], v[88:89]
	v_add_f32_dpp v90, v90, v90 quad_perm:[1,0,3,2] row_mask:0xf bank_mask:0xf bound_ctrl:1
	v_pk_fma_f32 v[84:85], v[76:77], v[70:71], v[80:81] op_sel_hi:[0,1,1]
	ds_read_b128 v[60:63], v110 offset:6912
	v_add_f32_dpp v90, v90, v90 quad_perm:[2,3,0,1] row_mask:0xf bank_mask:0xf bound_ctrl:1
	ds_read_b128 v[56:59], v110 offset:2816
	v_add_f32_e32 v102, v88, v89
	v_add_f32_dpp v90, v90, v90 row_half_mirror row_mask:0xf bank_mask:0xf bound_ctrl:1
	ds_read_b128 v[50:53], v110 offset:18944
	ds_read_b128 v[68:71], v110 offset:15104
	v_add_f32_dpp v92, v90, v90 row_mirror row_mask:0xf bank_mask:0xf bound_ctrl:1
	ds_read_b32 v76, v111 offset:23296
	v_pk_fma_f32 v[2:3], v[92:93], v[64:65], v[82:83] op_sel_hi:[0,1,1] neg_lo:[1,0,0] neg_hi:[1,0,0]
	v_pk_fma_f32 v[4:5], v[92:93], v[66:67], v[84:85] op_sel_hi:[0,1,1] neg_lo:[1,0,0] neg_hi:[1,0,0]
	ds_read_b128 v[64:67], v110 offset:11008
	s_waitcnt lgkmcnt(6)
	v_pk_mul_f32 v[86:87], v[2:3], v[38:39]
	v_pk_mul_f32 v[78:79], v[2:3], v[34:35]
	v_pk_fma_f32 v[86:87], v[4:5], v[40:41], v[86:87]
	v_pk_mul_f32 v[80:81], v[4:5], v[36:37]
	v_pk_mul_f32 v[88:89], v[2:3], v[72:73]
	v_add_f32_e32 v90, v86, v87
	v_pk_fma_f32 v[82:83], v[54:55], v[46:47], v[78:79] op_sel_hi:[0,1,1]
	v_pk_fma_f32 v[88:89], v[4:5], v[74:75], v[88:89]
	v_add_f32_dpp v90, v90, v90 quad_perm:[1,0,3,2] row_mask:0xf bank_mask:0xf bound_ctrl:1
	v_pk_fma_f32 v[84:85], v[54:55], v[48:49], v[80:81] op_sel_hi:[0,1,1]
	ds_read_b128 v[38:41], v110 offset:7168
	v_add_f32_dpp v90, v90, v90 quad_perm:[2,3,0,1] row_mask:0xf bank_mask:0xf bound_ctrl:1
	ds_read_b128 v[34:37], v110 offset:3072
	v_add_f32_e32 v103, v88, v89
	v_add_f32_dpp v90, v90, v90 row_half_mirror row_mask:0xf bank_mask:0xf bound_ctrl:1
	ds_read_b128 v[72:75], v110 offset:19200
	ds_read_b128 v[46:49], v110 offset:15360
	v_add_f32_dpp v92, v90, v90 row_mirror row_mask:0xf bank_mask:0xf bound_ctrl:1
	ds_read_b32 v54, v111 offset:23552
	v_pk_fma_f32 v[2:3], v[92:93], v[42:43], v[82:83] op_sel_hi:[0,1,1] neg_lo:[1,0,0] neg_hi:[1,0,0]
	v_pk_fma_f32 v[4:5], v[92:93], v[44:45], v[84:85] op_sel_hi:[0,1,1] neg_lo:[1,0,0] neg_hi:[1,0,0]
	ds_read_b128 v[42:45], v110 offset:11264
	s_waitcnt lgkmcnt(6)
	v_pk_mul_f32 v[86:87], v[2:3], v[60:61]
	v_pk_mul_f32 v[78:79], v[2:3], v[56:57]
	v_pk_fma_f32 v[86:87], v[4:5], v[62:63], v[86:87]
	v_pk_mul_f32 v[80:81], v[4:5], v[58:59]
	v_pk_mul_f32 v[88:89], v[2:3], v[50:51]
	v_add_f32_e32 v90, v86, v87
	v_pk_fma_f32 v[82:83], v[76:77], v[68:69], v[78:79] op_sel_hi:[0,1,1]
	v_pk_fma_f32 v[88:89], v[4:5], v[52:53], v[88:89]
	v_add_f32_dpp v90, v90, v90 quad_perm:[1,0,3,2] row_mask:0xf bank_mask:0xf bound_ctrl:1
	v_pk_fma_f32 v[84:85], v[76:77], v[70:71], v[80:81] op_sel_hi:[0,1,1]
	ds_read_b128 v[60:63], v110 offset:7424
	v_add_f32_dpp v90, v90, v90 quad_perm:[2,3,0,1] row_mask:0xf bank_mask:0xf bound_ctrl:1
	ds_read_b128 v[56:59], v110 offset:3328
	v_add_f32_e32 v104, v88, v89
	v_add_f32_dpp v90, v90, v90 row_half_mirror row_mask:0xf bank_mask:0xf bound_ctrl:1
	ds_read_b128 v[50:53], v110 offset:19456
	ds_read_b128 v[68:71], v110 offset:15616
	v_add_f32_dpp v92, v90, v90 row_mirror row_mask:0xf bank_mask:0xf bound_ctrl:1
	ds_read_b32 v76, v111 offset:23808
	v_pk_fma_f32 v[2:3], v[92:93], v[64:65], v[82:83] op_sel_hi:[0,1,1] neg_lo:[1,0,0] neg_hi:[1,0,0]
	v_pk_fma_f32 v[4:5], v[92:93], v[66:67], v[84:85] op_sel_hi:[0,1,1] neg_lo:[1,0,0] neg_hi:[1,0,0]
	ds_read_b128 v[64:67], v110 offset:11520
	s_waitcnt lgkmcnt(6)
	v_pk_mul_f32 v[86:87], v[2:3], v[38:39]
	v_pk_mul_f32 v[78:79], v[2:3], v[34:35]
	v_pk_fma_f32 v[86:87], v[4:5], v[40:41], v[86:87]
	v_pk_mul_f32 v[80:81], v[4:5], v[36:37]
	v_pk_mul_f32 v[88:89], v[2:3], v[72:73]
	v_add_f32_e32 v90, v86, v87
	v_pk_fma_f32 v[82:83], v[54:55], v[46:47], v[78:79] op_sel_hi:[0,1,1]
	v_pk_fma_f32 v[88:89], v[4:5], v[74:75], v[88:89]
	v_add_f32_dpp v90, v90, v90 quad_perm:[1,0,3,2] row_mask:0xf bank_mask:0xf bound_ctrl:1
	v_pk_fma_f32 v[84:85], v[54:55], v[48:49], v[80:81] op_sel_hi:[0,1,1]
	ds_read_b128 v[38:41], v110 offset:7680
	v_add_f32_dpp v90, v90, v90 quad_perm:[2,3,0,1] row_mask:0xf bank_mask:0xf bound_ctrl:1
	ds_read_b128 v[34:37], v110 offset:3584
	v_add_f32_e32 v105, v88, v89
	v_add_f32_dpp v90, v90, v90 row_half_mirror row_mask:0xf bank_mask:0xf bound_ctrl:1
	ds_read_b128 v[72:75], v110 offset:19712
	ds_read_b128 v[46:49], v110 offset:15872
	v_add_f32_dpp v92, v90, v90 row_mirror row_mask:0xf bank_mask:0xf bound_ctrl:1
	ds_read_b32 v54, v111 offset:24064
	v_pk_fma_f32 v[2:3], v[92:93], v[42:43], v[82:83] op_sel_hi:[0,1,1] neg_lo:[1,0,0] neg_hi:[1,0,0]
	v_pk_fma_f32 v[4:5], v[92:93], v[44:45], v[84:85] op_sel_hi:[0,1,1] neg_lo:[1,0,0] neg_hi:[1,0,0]
	ds_read_b128 v[42:45], v110 offset:11776
	s_waitcnt lgkmcnt(6)
	v_pk_mul_f32 v[86:87], v[2:3], v[60:61]
	v_pk_mul_f32 v[78:79], v[2:3], v[56:57]
	v_pk_fma_f32 v[86:87], v[4:5], v[62:63], v[86:87]
	v_pk_mul_f32 v[80:81], v[4:5], v[58:59]
	v_pk_mul_f32 v[88:89], v[2:3], v[50:51]
	v_add_f32_e32 v90, v86, v87
	v_pk_fma_f32 v[82:83], v[76:77], v[68:69], v[78:79] op_sel_hi:[0,1,1]
	v_pk_fma_f32 v[88:89], v[4:5], v[52:53], v[88:89]
	v_add_f32_dpp v90, v90, v90 quad_perm:[1,0,3,2] row_mask:0xf bank_mask:0xf bound_ctrl:1
	v_pk_fma_f32 v[84:85], v[76:77], v[70:71], v[80:81] op_sel_hi:[0,1,1]
	ds_read_b128 v[60:63], v110 offset:7936
	v_add_f32_dpp v90, v90, v90 quad_perm:[2,3,0,1] row_mask:0xf bank_mask:0xf bound_ctrl:1
	ds_read_b128 v[56:59], v110 offset:3840
	v_add_f32_e32 v106, v88, v89
	v_add_f32_dpp v90, v90, v90 row_half_mirror row_mask:0xf bank_mask:0xf bound_ctrl:1
	ds_read_b128 v[50:53], v110 offset:19968
	ds_read_b128 v[68:71], v110 offset:16128
	v_add_f32_dpp v92, v90, v90 row_mirror row_mask:0xf bank_mask:0xf bound_ctrl:1
	ds_read_b32 v76, v111 offset:24320
	s_cmpk_eq_i32 s33, 0x10f
	s_cbranch_scc1 .Lscan_tail_last
	v_pk_fma_f32 v[2:3], v[92:93], v[64:65], v[82:83] op_sel_hi:[0,1,1] neg_lo:[1,0,0] neg_hi:[1,0,0]
	v_pk_fma_f32 v[4:5], v[92:93], v[66:67], v[84:85] op_sel_hi:[0,1,1] neg_lo:[1,0,0] neg_hi:[1,0,0]
	ds_read_b128 v[64:67], v110 offset:12032
	s_waitcnt lgkmcnt(6)
	v_pk_mul_f32 v[86:87], v[2:3], v[38:39]
	v_pk_mul_f32 v[78:79], v[2:3], v[34:35]
	v_pk_fma_f32 v[86:87], v[4:5], v[40:41], v[86:87]
	v_pk_mul_f32 v[80:81], v[4:5], v[36:37]
	v_pk_mul_f32 v[88:89], v[2:3], v[72:73]
	v_add_f32_e32 v90, v86, v87
	v_pk_fma_f32 v[82:83], v[54:55], v[46:47], v[78:79] op_sel_hi:[0,1,1]
	v_pk_fma_f32 v[88:89], v[4:5], v[74:75], v[88:89]
	v_add_f32_dpp v90, v90, v90 quad_perm:[1,0,3,2] row_mask:0xf bank_mask:0xf bound_ctrl:1
	v_pk_fma_f32 v[84:85], v[54:55], v[48:49], v[80:81] op_sel_hi:[0,1,1]
	s_waitcnt vmcnt(6)
	v_add_f32_dpp v90, v90, v90 quad_perm:[2,3,0,1] row_mask:0xf bank_mask:0xf bound_ctrl:1
	v_pk_add_f32 v[122:123], v[150:151], -1.0 op_sel_hi:[1,0]
	v_add_f32_e32 v107, v88, v89
	v_add_f32_dpp v90, v90, v90 row_half_mirror row_mask:0xf bank_mask:0xf bound_ctrl:1
	ds_read_b128 v[72:75], v110 offset:20224
	v_pk_add_f32 v[124:125], v[152:153], -1.0 op_sel_hi:[1,0]
	v_add_f32_dpp v92, v90, v90 row_mirror row_mask:0xf bank_mask:0xf bound_ctrl:1
	v_pk_mul_f32 v[118:119], v[154:155], v[150:151]
	v_pk_fma_f32 v[2:3], v[92:93], v[42:43], v[82:83] op_sel_hi:[0,1,1] neg_lo:[1,0,0] neg_hi:[1,0,0]
	v_pk_fma_f32 v[4:5], v[92:93], v[44:45], v[84:85] op_sel_hi:[0,1,1] neg_lo:[1,0,0] neg_hi:[1,0,0]
	v_pk_fma_f32 v[122:123], v[6:7], v[122:123], 1.0 op_sel_hi:[1,1,0]
	s_waitcnt lgkmcnt(1)
	v_pk_mul_f32 v[86:87], v[2:3], v[60:61]
	v_pk_mul_f32 v[78:79], v[2:3], v[56:57]
	v_pk_fma_f32 v[86:87], v[4:5], v[62:63], v[86:87]
	v_pk_mul_f32 v[80:81], v[4:5], v[58:59]
	v_pk_mul_f32 v[88:89], v[2:3], v[50:51]
	v_add_f32_e32 v90, v86, v87
	v_pk_fma_f32 v[82:83], v[76:77], v[68:69], v[78:79] op_sel_hi:[0,1,1]
	v_pk_fma_f32 v[88:89], v[4:5], v[52:53], v[88:89]
	v_add_f32_dpp v90, v90, v90 quad_perm:[1,0,3,2] row_mask:0xf bank_mask:0xf bound_ctrl:1
	v_pk_fma_f32 v[84:85], v[76:77], v[70:71], v[80:81] op_sel_hi:[0,1,1]
	v_pk_fma_f32 v[124:125], v[8:9], v[124:125], 1.0 op_sel_hi:[1,1,0]
	v_add_f32_dpp v90, v90, v90 quad_perm:[2,3,0,1] row_mask:0xf bank_mask:0xf bound_ctrl:1
	v_pk_mul_f32 v[120:121], v[156:157], v[152:153]
	v_add_f32_e32 v108, v88, v89
	v_add_f32_dpp v90, v90, v90 row_half_mirror row_mask:0xf bank_mask:0xf bound_ctrl:1
	v_pk_mul_f32 v[122:123], v[138:139], v[122:123]
	v_pk_mul_f32 v[124:125], v[140:141], v[124:125]
	v_add_f32_dpp v92, v90, v90 row_mirror row_mask:0xf bank_mask:0xf bound_ctrl:1
	ds_write_b128 v112, v[146:149] offset:0
	ds_write_b128 v112, v[154:157] offset:4096
	v_pk_fma_f32 v[2:3], v[92:93], v[64:65], v[82:83] op_sel_hi:[0,1,1] neg_lo:[1,0,0] neg_hi:[1,0,0]
	v_pk_fma_f32 v[4:5], v[92:93], v[66:67], v[84:85] op_sel_hi:[0,1,1] neg_lo:[1,0,0] neg_hi:[1,0,0]
	ds_write_b128 v112, v[134:137] offset:16384
	s_waitcnt lgkmcnt(3)
	v_pk_mul_f32 v[88:89], v[2:3], v[72:73]
	ds_write_b128 v112, v[142:145] offset:20480
	v_pk_fma_f32 v[88:89], v[4:5], v[74:75], v[88:89]
	ds_write_b128 v112, v[118:121] offset:8192
	v_add_f32_e32 v109, v88, v89
	ds_write_b128 v112, v[122:125] offset:12288
	s_waitcnt lgkmcnt(0)
	v_xor_b32_e32 v110, 0x6000, v110
	v_xor_b32_e32 v111, 0x6000, v111
	v_xor_b32_e32 v112, 0x6000, v112
	s_add_i32 s33, s33, 1
	s_barrier
	ds_read_b128 v[38:41], v110 offset:4096
	ds_read_b128 v[34:37], v110 offset:0
	ds_read_b128 v[46:49], v110 offset:12288
	ds_read_b32 v54, v111 offset:20480
	ds_read_b128 v[42:45], v110 offset:8192
	ds_read_b128 v[50:53], v110 offset:16384
	ds_read_b128 v[60:63], v110 offset:4352
	ds_read_b128 v[56:59], v110 offset:256
	ds_read_b128 v[68:71], v110 offset:12544
	ds_read_b32 v76, v111 offset:20736
	ds_read_b128 v[64:67], v110 offset:8448
	ds_read_b128 v[72:75], v110 offset:16640
	s_cmpk_ge_i32 s33, 0x10e
	s_cbranch_scc1 .Lscan_skipload_b
	v_mul_u32_u24_e32 v0, 0xf00, v113
	v_lshl_add_u32 v125, v113, 10, v115
	v_add_u32_e32 v0, v0, v115
	v_add_u32_e32 v113, s34, v113
	global_load_dwordx4 v[146:149], v125, s[46:47] sc1
	global_load_dwordx4 v[150:153], v125, s[48:49] sc1
	global_load_dwordx4 v[154:157], v125, s[22:23] sc1
	global_load_dwordx4 v[138:141], v0, s[12:13] offset:1024 sc1
	global_load_dwordx4 v[134:137], v0, s[12:13] sc1
	global_load_dwordx4 v[142:145], v0, s[12:13] offset:2048 sc1
	s_cmp_eq_u32 s33, 13
	s_cbranch_scc0 .Lscan_nogload_b
	v_mov_b32_e32 v113, v117
	s_branch .Lscan_nogload_b
